# GEMM load segments: LDS-DMA issue moved ahead of the fragment ds_reads (more prefetch lead), on top of v36
# baseline (speedup 1.0000x reference)
.Lpeela:
	s_add_u32 s52, s50, 0xfff00080
	s_addc_u32 s53, s51, -1
	s_cmp_eq_u32 s89, 60
	s_cselect_b32 s55, s43, s53
	s_cselect_b32 s54, s85, s52
	s_cselect_b32 s53, s41, s88
	s_cselect_b32 s52, s86, s87
	v_lshl_add_u64 v[204:205], s[50:51], 0, v[192:193]
	s_add_i32 m0, s56, 0xc000
	s_nop 0
	global_load_lds_dwordx4 v[204:205], off
	v_lshl_add_u64 v[204:205], s[50:51], 0, v[194:195]
	s_add_i32 m0, s56, 0xe000
	s_nop 0
	global_load_lds_dwordx4 v[204:205], off
	ds_read_b128 v[130:133], v208
	ds_read_b128 v[134:137], v208 offset:1024
	ds_read_b128 v[138:141], v208 offset:2048
	ds_read_b128 v[142:145], v208 offset:3072
	ds_read_b128 v[146:149], v209
	ds_read_b128 v[150:153], v209 offset:1024
	ds_read_b128 v[154:157], v209 offset:2048
	ds_read_b128 v[158:161], v209 offset:3072
	ds_read_b128 v[162:165], v210
	ds_read_b128 v[166:169], v210 offset:1024
	ds_read_b128 v[170:173], v210 offset:2048
	ds_read_b128 v[174:177], v210 offset:3072
	ds_read_b128 v[200:203], v210 offset:4096
	ds_read_b128 v[212:215], v210 offset:5120
	ds_read_b128 v[216:219], v210 offset:6144
	ds_read_b128 v[224:227], v210 offset:7168
	s_waitcnt vmcnt(8)
	s_waitcnt lgkmcnt(0)
	s_setprio 1
	s_barrier
	v_mfma_f32_16x16x32_bf16 v[126:129], v[130:133], v[162:165], 0
	v_mfma_f32_16x16x32_bf16 v[122:125], v[138:141], v[162:165], 0
	v_mfma_f32_16x16x32_bf16 v[110:113], v[130:133], v[170:173], 0
	v_mfma_f32_16x16x32_bf16 v[106:109], v[138:141], v[170:173], 0
	v_mfma_f32_16x16x32_bf16 v[94:97], v[130:133], v[200:203], 0
	v_mfma_f32_16x16x32_bf16 v[90:93], v[138:141], v[200:203], 0
	v_mfma_f32_16x16x32_bf16 v[78:81], v[130:133], v[216:219], 0
	v_mfma_f32_16x16x32_bf16 v[74:77], v[138:141], v[216:219], 0
	v_mfma_f32_16x16x32_bf16 v[126:129], v[134:137], v[166:169], v[126:129]
	v_mfma_f32_16x16x32_bf16 v[122:125], v[142:145], v[166:169], v[122:125]
	v_mfma_f32_16x16x32_bf16 v[110:113], v[134:137], v[174:177], v[110:113]
	v_mfma_f32_16x16x32_bf16 v[106:109], v[142:145], v[174:177], v[106:109]
	v_mfma_f32_16x16x32_bf16 v[94:97], v[134:137], v[212:215], v[94:97]
	v_mfma_f32_16x16x32_bf16 v[90:93], v[142:145], v[212:215], v[90:93]
	v_mfma_f32_16x16x32_bf16 v[78:81], v[134:137], v[224:227], v[78:81]
	v_mfma_f32_16x16x32_bf16 v[74:77], v[142:145], v[224:227], v[74:77]
	v_mfma_f32_16x16x32_bf16 v[118:121], v[146:149], v[162:165], 0
	v_mfma_f32_16x16x32_bf16 v[114:117], v[154:157], v[162:165], 0
	v_mfma_f32_16x16x32_bf16 v[102:105], v[146:149], v[170:173], 0
	v_mfma_f32_16x16x32_bf16 v[98:101], v[154:157], v[170:173], 0
	v_mfma_f32_16x16x32_bf16 v[86:89], v[146:149], v[200:203], 0
	v_mfma_f32_16x16x32_bf16 v[82:85], v[154:157], v[200:203], 0
	v_mfma_f32_16x16x32_bf16 v[70:73], v[146:149], v[216:219], 0
	v_mfma_f32_16x16x32_bf16 v[66:69], v[154:157], v[216:219], 0
	v_mfma_f32_16x16x32_bf16 v[118:121], v[150:153], v[166:169], v[118:121]
	v_mfma_f32_16x16x32_bf16 v[114:117], v[158:161], v[166:169], v[114:117]
	v_mfma_f32_16x16x32_bf16 v[102:105], v[150:153], v[174:177], v[102:105]
	v_mfma_f32_16x16x32_bf16 v[98:101], v[158:161], v[174:177], v[98:101]
	v_mfma_f32_16x16x32_bf16 v[86:89], v[150:153], v[212:215], v[86:89]
	v_mfma_f32_16x16x32_bf16 v[82:85], v[158:161], v[212:215], v[82:85]
	v_mfma_f32_16x16x32_bf16 v[70:73], v[150:153], v[224:227], v[70:73]
	v_mfma_f32_16x16x32_bf16 v[66:69], v[158:161], v[224:227], v[66:69]
	s_barrier
	s_setprio 0
	s_add_i32 s90, s65, s31
	v_lshl_add_u64 v[204:205], s[52:53], 0, v[182:183]
	s_mov_b32 m0, s90
	s_nop 0
	global_load_lds_dwordx4 v[204:205], off
	s_add_i32 m0, s90, 0x2000
	s_add_u32 s90, s52, 0x100000
	v_lshl_add_u64 v[220:221], s[52:53], 0, v[178:179]
	s_addc_u32 s91, s53, 0
	s_add_i32 s92, s66, s31
	global_load_lds_dwordx4 v[220:221], off
	v_lshl_add_u64 v[228:229], s[90:91], 0, v[182:183]
	s_mov_b32 m0, s92
	v_lshl_add_u64 v[230:231], s[54:55], 0, v[180:181]
	global_load_lds_dwordx4 v[228:229], off
	v_lshl_add_u64 v[228:229], s[90:91], 0, v[178:179]
	s_add_i32 m0, s92, 0x2000
	s_nop 0
	global_load_lds_dwordx4 v[228:229], off
	v_lshl_add_u64 v[228:229], s[54:55], 0, v[184:185]
	s_mov_b32 m0, s56
	s_nop 0
	global_load_lds_dwordx4 v[228:229], off
	s_mov_b32 m0, s57
	s_nop 0
	global_load_lds_dwordx4 v[230:231], off
	ds_read_b128 v[162:165], v210 offset:16384
	ds_read_b128 v[166:169], v210 offset:17408
	ds_read_b128 v[170:173], v210 offset:18432
	ds_read_b128 v[174:177], v210 offset:19456
	ds_read_b128 v[200:203], v210 offset:20480
	ds_read_b128 v[212:215], v210 offset:21504
	ds_read_b128 v[216:219], v210 offset:22528
	ds_read_b128 v[224:227], v210 offset:23552
	s_waitcnt vmcnt(8)
	s_waitcnt lgkmcnt(0)
	s_setprio 1
	s_barrier
	v_mfma_f32_16x16x32_bf16 v[62:65], v[130:133], v[162:165], 0
	v_mfma_f32_16x16x32_bf16 v[58:61], v[138:141], v[162:165], 0
	v_mfma_f32_16x16x32_bf16 v[50:53], v[130:133], v[170:173], 0
	v_mfma_f32_16x16x32_bf16 v[42:45], v[138:141], v[170:173], 0
	v_mfma_f32_16x16x32_bf16 v[34:37], v[130:133], v[200:203], 0
	v_mfma_f32_16x16x32_bf16 v[26:29], v[138:141], v[200:203], 0
	v_mfma_f32_16x16x32_bf16 v[18:21], v[130:133], v[216:219], 0
	v_mfma_f32_16x16x32_bf16 v[10:13], v[138:141], v[216:219], 0
	v_mfma_f32_16x16x32_bf16 v[62:65], v[134:137], v[166:169], v[62:65]
	v_mfma_f32_16x16x32_bf16 v[58:61], v[142:145], v[166:169], v[58:61]
	v_mfma_f32_16x16x32_bf16 v[50:53], v[134:137], v[174:177], v[50:53]
	v_mfma_f32_16x16x32_bf16 v[42:45], v[142:145], v[174:177], v[42:45]
	v_mfma_f32_16x16x32_bf16 v[34:37], v[134:137], v[212:215], v[34:37]
	v_mfma_f32_16x16x32_bf16 v[26:29], v[142:145], v[212:215], v[26:29]
	v_mfma_f32_16x16x32_bf16 v[18:21], v[134:137], v[224:227], v[18:21]
	v_mfma_f32_16x16x32_bf16 v[10:13], v[142:145], v[224:227], v[10:13]
	v_mfma_f32_16x16x32_bf16 v[54:57], v[146:149], v[162:165], 0
	v_mfma_f32_16x16x32_bf16 v[46:49], v[154:157], v[162:165], 0
	v_mfma_f32_16x16x32_bf16 v[38:41], v[146:149], v[170:173], 0
	v_mfma_f32_16x16x32_bf16 v[30:33], v[154:157], v[170:173], 0
	v_mfma_f32_16x16x32_bf16 v[22:25], v[146:149], v[200:203], 0
	v_mfma_f32_16x16x32_bf16 v[14:17], v[154:157], v[200:203], 0
	v_mfma_f32_16x16x32_bf16 v[6:9], v[146:149], v[216:219], 0
	v_mfma_f32_16x16x32_bf16 v[2:5], v[154:157], v[216:219], 0
	v_mfma_f32_16x16x32_bf16 v[54:57], v[150:153], v[166:169], v[54:57]
	v_mfma_f32_16x16x32_bf16 v[46:49], v[158:161], v[166:169], v[46:49]
	v_mfma_f32_16x16x32_bf16 v[38:41], v[150:153], v[174:177], v[38:41]
	v_mfma_f32_16x16x32_bf16 v[30:33], v[158:161], v[174:177], v[30:33]
	v_mfma_f32_16x16x32_bf16 v[22:25], v[150:153], v[212:215], v[22:25]
	v_mfma_f32_16x16x32_bf16 v[14:17], v[158:161], v[212:215], v[14:17]
	v_mfma_f32_16x16x32_bf16 v[6:9], v[150:153], v[224:227], v[6:9]
	v_mfma_f32_16x16x32_bf16 v[2:5], v[158:161], v[224:227], v[2:5]
	s_barrier
	s_setprio 0
	s_add_i32 s90, 0, 0x18000
	s_add_i32 s91, 0, 0x1c000
	v_add_u32_e32 v142, s90, v189
	v_add_u32_e32 v158, s91, v189
	s_add_u32 s54, s54, 0x100000
	s_addc_u32 s55, s55, 0
	s_mov_b32 m0, s58
	v_lshl_add_u64 v[232:233], s[54:55], 0, v[184:185]
	global_load_lds_dwordx4 v[232:233], off
	v_lshl_add_u64 v[232:233], s[54:55], 0, v[180:181]
	s_mov_b32 m0, s59
	s_nop 0
	global_load_lds_dwordx4 v[232:233], off
	ds_read_b128 v[130:133], v142
	ds_read_b128 v[134:137], v142 offset:1024
	ds_read_b128 v[138:141], v142 offset:2048
	ds_read_b128 v[142:145], v142 offset:3072
	ds_read_b128 v[146:149], v158
	ds_read_b128 v[150:153], v158 offset:1024
	ds_read_b128 v[154:157], v158 offset:2048
	ds_read_b128 v[158:161], v158 offset:3072
	ds_read_b128 v[162:165], v210 offset:32768
	ds_read_b128 v[166:169], v210 offset:33792
	ds_read_b128 v[170:173], v210 offset:34816
	ds_read_b128 v[174:177], v210 offset:35840
	ds_read_b128 v[200:203], v210 offset:36864
	ds_read_b128 v[212:215], v210 offset:37888
	ds_read_b128 v[216:219], v210 offset:38912
	ds_read_b128 v[224:227], v210 offset:39936
	s_waitcnt vmcnt(8)
	s_waitcnt lgkmcnt(0)
	s_setprio 1
	s_barrier
	v_mfma_f32_16x16x32_bf16 v[126:129], v[130:133], v[162:165], v[126:129]
	v_mfma_f32_16x16x32_bf16 v[122:125], v[138:141], v[162:165], v[122:125]
	v_mfma_f32_16x16x32_bf16 v[110:113], v[130:133], v[170:173], v[110:113]
	v_mfma_f32_16x16x32_bf16 v[106:109], v[138:141], v[170:173], v[106:109]
	v_mfma_f32_16x16x32_bf16 v[94:97], v[130:133], v[200:203], v[94:97]
	v_mfma_f32_16x16x32_bf16 v[90:93], v[138:141], v[200:203], v[90:93]
	v_mfma_f32_16x16x32_bf16 v[78:81], v[130:133], v[216:219], v[78:81]
	v_mfma_f32_16x16x32_bf16 v[74:77], v[138:141], v[216:219], v[74:77]
	v_mfma_f32_16x16x32_bf16 v[126:129], v[134:137], v[166:169], v[126:129]
	v_mfma_f32_16x16x32_bf16 v[122:125], v[142:145], v[166:169], v[122:125]
	v_mfma_f32_16x16x32_bf16 v[110:113], v[134:137], v[174:177], v[110:113]
	v_mfma_f32_16x16x32_bf16 v[106:109], v[142:145], v[174:177], v[106:109]
	v_mfma_f32_16x16x32_bf16 v[94:97], v[134:137], v[212:215], v[94:97]
	v_mfma_f32_16x16x32_bf16 v[90:93], v[142:145], v[212:215], v[90:93]
	v_mfma_f32_16x16x32_bf16 v[78:81], v[134:137], v[224:227], v[78:81]
	v_mfma_f32_16x16x32_bf16 v[74:77], v[142:145], v[224:227], v[74:77]
	v_mfma_f32_16x16x32_bf16 v[118:121], v[146:149], v[162:165], v[118:121]
	v_mfma_f32_16x16x32_bf16 v[114:117], v[154:157], v[162:165], v[114:117]
	v_mfma_f32_16x16x32_bf16 v[102:105], v[146:149], v[170:173], v[102:105]
	v_mfma_f32_16x16x32_bf16 v[98:101], v[154:157], v[170:173], v[98:101]
	v_mfma_f32_16x16x32_bf16 v[86:89], v[146:149], v[200:203], v[86:89]
	v_mfma_f32_16x16x32_bf16 v[82:85], v[154:157], v[200:203], v[82:85]
	v_mfma_f32_16x16x32_bf16 v[70:73], v[146:149], v[216:219], v[70:73]
	v_mfma_f32_16x16x32_bf16 v[66:69], v[154:157], v[216:219], v[66:69]
	v_mfma_f32_16x16x32_bf16 v[118:121], v[150:153], v[166:169], v[118:121]
	v_mfma_f32_16x16x32_bf16 v[114:117], v[158:161], v[166:169], v[114:117]
	v_mfma_f32_16x16x32_bf16 v[102:105], v[150:153], v[174:177], v[102:105]
	v_mfma_f32_16x16x32_bf16 v[98:101], v[158:161], v[174:177], v[98:101]
	v_mfma_f32_16x16x32_bf16 v[86:89], v[150:153], v[212:215], v[86:89]
	v_mfma_f32_16x16x32_bf16 v[82:85], v[158:161], v[212:215], v[82:85]
	v_mfma_f32_16x16x32_bf16 v[70:73], v[150:153], v[224:227], v[70:73]
	v_mfma_f32_16x16x32_bf16 v[66:69], v[158:161], v[224:227], v[66:69]
	s_barrier
	s_setprio 0
	s_add_i32 s54, s90, s31
	v_lshl_add_u64 v[204:205], v[204:205], 0, s[8:9]
	s_mov_b32 m0, s54
	s_nop 0
	global_load_lds_dwordx4 v[204:205], off
	s_add_i32 m0, s54, 0x2000
	s_add_u32 s52, s52, 0x100080
	v_lshl_add_u64 v[204:205], v[220:221], 0, s[8:9]
	s_addc_u32 s53, s53, 0
	s_add_i32 s54, s91, s31
	global_load_lds_dwordx4 v[204:205], off
	v_lshl_add_u64 v[204:205], s[52:53], 0, v[182:183]
	s_mov_b32 m0, s54
	s_nop 0
	global_load_lds_dwordx4 v[204:205], off
	v_lshl_add_u64 v[204:205], s[52:53], 0, v[178:179]
	s_add_i32 m0, s54, 0x2000
	s_nop 0
	global_load_lds_dwordx4 v[204:205], off
	v_lshl_add_u64 v[204:205], v[228:229], 0, s[8:9]
	s_mov_b32 m0, s62
	s_nop 0
	global_load_lds_dwordx4 v[204:205], off
	v_lshl_add_u64 v[204:205], v[230:231], 0, s[8:9]
	s_mov_b32 m0, s63
	s_nop 0
	global_load_lds_dwordx4 v[204:205], off
	ds_read_b128 v[162:165], v210 offset:49152
	ds_read_b128 v[166:169], v210 offset:50176
	ds_read_b128 v[170:173], v210 offset:51200
	ds_read_b128 v[174:177], v210 offset:52224
	ds_read_b128 v[200:203], v210 offset:53248
	ds_read_b128 v[212:215], v210 offset:54272
	ds_read_b128 v[216:219], v210 offset:55296
	ds_read_b128 v[224:227], v210 offset:56320
	s_waitcnt vmcnt(8)
	s_waitcnt lgkmcnt(0)
	s_setprio 1
	s_barrier
	v_mfma_f32_16x16x32_bf16 v[62:65], v[130:133], v[162:165], v[62:65]
	v_mfma_f32_16x16x32_bf16 v[58:61], v[138:141], v[162:165], v[58:61]
	v_mfma_f32_16x16x32_bf16 v[50:53], v[130:133], v[170:173], v[50:53]
	v_mfma_f32_16x16x32_bf16 v[42:45], v[138:141], v[170:173], v[42:45]
	v_mfma_f32_16x16x32_bf16 v[34:37], v[130:133], v[200:203], v[34:37]
	v_mfma_f32_16x16x32_bf16 v[26:29], v[138:141], v[200:203], v[26:29]
	v_mfma_f32_16x16x32_bf16 v[18:21], v[130:133], v[216:219], v[18:21]
	v_mfma_f32_16x16x32_bf16 v[10:13], v[138:141], v[216:219], v[10:13]
	v_mfma_f32_16x16x32_bf16 v[62:65], v[134:137], v[166:169], v[62:65]
	v_mfma_f32_16x16x32_bf16 v[58:61], v[142:145], v[166:169], v[58:61]
	v_mfma_f32_16x16x32_bf16 v[50:53], v[134:137], v[174:177], v[50:53]
	v_mfma_f32_16x16x32_bf16 v[42:45], v[142:145], v[174:177], v[42:45]
	v_mfma_f32_16x16x32_bf16 v[34:37], v[134:137], v[212:215], v[34:37]
	v_mfma_f32_16x16x32_bf16 v[26:29], v[142:145], v[212:215], v[26:29]
	v_mfma_f32_16x16x32_bf16 v[18:21], v[134:137], v[224:227], v[18:21]
	v_mfma_f32_16x16x32_bf16 v[10:13], v[142:145], v[224:227], v[10:13]
	v_mfma_f32_16x16x32_bf16 v[54:57], v[146:149], v[162:165], v[54:57]
	v_mfma_f32_16x16x32_bf16 v[46:49], v[154:157], v[162:165], v[46:49]
	v_mfma_f32_16x16x32_bf16 v[38:41], v[146:149], v[170:173], v[38:41]
	v_mfma_f32_16x16x32_bf16 v[30:33], v[154:157], v[170:173], v[30:33]
	v_mfma_f32_16x16x32_bf16 v[22:25], v[146:149], v[200:203], v[22:25]
	v_mfma_f32_16x16x32_bf16 v[14:17], v[154:157], v[200:203], v[14:17]
	v_mfma_f32_16x16x32_bf16 v[6:9], v[146:149], v[216:219], v[6:9]
	v_mfma_f32_16x16x32_bf16 v[2:5], v[154:157], v[216:219], v[2:5]
	v_mfma_f32_16x16x32_bf16 v[54:57], v[150:153], v[166:169], v[54:57]
	v_mfma_f32_16x16x32_bf16 v[46:49], v[158:161], v[166:169], v[46:49]
	v_mfma_f32_16x16x32_bf16 v[38:41], v[150:153], v[174:177], v[38:41]
	v_mfma_f32_16x16x32_bf16 v[30:33], v[158:161], v[174:177], v[30:33]
	v_mfma_f32_16x16x32_bf16 v[22:25], v[150:153], v[212:215], v[22:25]
	v_mfma_f32_16x16x32_bf16 v[14:17], v[158:161], v[212:215], v[14:17]
	v_mfma_f32_16x16x32_bf16 v[6:9], v[150:153], v[224:227], v[6:9]
	v_mfma_f32_16x16x32_bf16 v[2:5], v[158:161], v[224:227], v[2:5]
	s_barrier
	s_setprio 0
	s_add_i32 s89, s89, 2
	s_add_u32 s50, s50, 0x100
	s_addc_u32 s51, s51, 0
	s_add_u32 s87, s87, 0x100
	s_addc_u32 s88, s88, 0
.LBB0_224:
	s_add_u32 s52, s50, 0xfff00080
	s_addc_u32 s53, s51, -1
	s_cmp_eq_u32 s89, 60
	s_cselect_b32 s55, s43, s53
	s_cselect_b32 s54, s85, s52
	s_cselect_b32 s53, s41, s88
	s_cselect_b32 s52, s86, s87
	v_lshl_add_u64 v[204:205], s[50:51], 0, v[192:193]
	s_add_i32 m0, s56, 0xc000
	s_nop 0
	global_load_lds_dwordx4 v[204:205], off
	v_lshl_add_u64 v[204:205], s[50:51], 0, v[194:195]
	s_add_i32 m0, s56, 0xe000
	s_nop 0
	global_load_lds_dwordx4 v[204:205], off
	ds_read_b128 v[130:133], v208
	ds_read_b128 v[134:137], v208 offset:1024
	ds_read_b128 v[138:141], v208 offset:2048
	ds_read_b128 v[142:145], v208 offset:3072
	ds_read_b128 v[146:149], v209
	ds_read_b128 v[150:153], v209 offset:1024
	ds_read_b128 v[154:157], v209 offset:2048
	ds_read_b128 v[158:161], v209 offset:3072
	ds_read_b128 v[162:165], v210
	ds_read_b128 v[166:169], v210 offset:1024
	ds_read_b128 v[170:173], v210 offset:2048
	ds_read_b128 v[174:177], v210 offset:3072
	ds_read_b128 v[200:203], v210 offset:4096
	ds_read_b128 v[212:215], v210 offset:5120
	ds_read_b128 v[216:219], v210 offset:6144
	ds_read_b128 v[224:227], v210 offset:7168
	s_waitcnt vmcnt(8)
	s_waitcnt lgkmcnt(0)
	s_setprio 1
	s_barrier
	v_mfma_f32_16x16x32_bf16 v[126:129], v[130:133], v[162:165], v[126:129]
	v_mfma_f32_16x16x32_bf16 v[122:125], v[138:141], v[162:165], v[122:125]
	v_mfma_f32_16x16x32_bf16 v[110:113], v[130:133], v[170:173], v[110:113]
	v_mfma_f32_16x16x32_bf16 v[106:109], v[138:141], v[170:173], v[106:109]
	v_mfma_f32_16x16x32_bf16 v[94:97], v[130:133], v[200:203], v[94:97]
	v_mfma_f32_16x16x32_bf16 v[90:93], v[138:141], v[200:203], v[90:93]
	v_mfma_f32_16x16x32_bf16 v[78:81], v[130:133], v[216:219], v[78:81]
	v_mfma_f32_16x16x32_bf16 v[74:77], v[138:141], v[216:219], v[74:77]
	v_mfma_f32_16x16x32_bf16 v[126:129], v[134:137], v[166:169], v[126:129]
	v_mfma_f32_16x16x32_bf16 v[122:125], v[142:145], v[166:169], v[122:125]
	v_mfma_f32_16x16x32_bf16 v[110:113], v[134:137], v[174:177], v[110:113]
	v_mfma_f32_16x16x32_bf16 v[106:109], v[142:145], v[174:177], v[106:109]
	v_mfma_f32_16x16x32_bf16 v[94:97], v[134:137], v[212:215], v[94:97]
	v_mfma_f32_16x16x32_bf16 v[90:93], v[142:145], v[212:215], v[90:93]
	v_mfma_f32_16x16x32_bf16 v[78:81], v[134:137], v[224:227], v[78:81]
	v_mfma_f32_16x16x32_bf16 v[74:77], v[142:145], v[224:227], v[74:77]
	v_mfma_f32_16x16x32_bf16 v[118:121], v[146:149], v[162:165], v[118:121]
	v_mfma_f32_16x16x32_bf16 v[114:117], v[154:157], v[162:165], v[114:117]
	v_mfma_f32_16x16x32_bf16 v[102:105], v[146:149], v[170:173], v[102:105]
	v_mfma_f32_16x16x32_bf16 v[98:101], v[154:157], v[170:173], v[98:101]
	v_mfma_f32_16x16x32_bf16 v[86:89], v[146:149], v[200:203], v[86:89]
	v_mfma_f32_16x16x32_bf16 v[82:85], v[154:157], v[200:203], v[82:85]
	v_mfma_f32_16x16x32_bf16 v[70:73], v[146:149], v[216:219], v[70:73]
	v_mfma_f32_16x16x32_bf16 v[66:69], v[154:157], v[216:219], v[66:69]
	v_mfma_f32_16x16x32_bf16 v[118:121], v[150:153], v[166:169], v[118:121]
	v_mfma_f32_16x16x32_bf16 v[114:117], v[158:161], v[166:169], v[114:117]
	v_mfma_f32_16x16x32_bf16 v[102:105], v[150:153], v[174:177], v[102:105]
	v_mfma_f32_16x16x32_bf16 v[98:101], v[158:161], v[174:177], v[98:101]
	v_mfma_f32_16x16x32_bf16 v[86:89], v[150:153], v[212:215], v[86:89]
	v_mfma_f32_16x16x32_bf16 v[82:85], v[158:161], v[212:215], v[82:85]
	v_mfma_f32_16x16x32_bf16 v[70:73], v[150:153], v[224:227], v[70:73]
	v_mfma_f32_16x16x32_bf16 v[66:69], v[158:161], v[224:227], v[66:69]
	s_barrier
	s_setprio 0
	s_add_i32 s90, s65, s31
	v_lshl_add_u64 v[204:205], s[52:53], 0, v[182:183]
	s_mov_b32 m0, s90
	s_nop 0
	global_load_lds_dwordx4 v[204:205], off
	s_add_i32 m0, s90, 0x2000
	s_add_u32 s90, s52, 0x100000
	v_lshl_add_u64 v[220:221], s[52:53], 0, v[178:179]
	s_addc_u32 s91, s53, 0
	s_add_i32 s92, s66, s31
	global_load_lds_dwordx4 v[220:221], off
	v_lshl_add_u64 v[228:229], s[90:91], 0, v[182:183]
	s_mov_b32 m0, s92
	v_lshl_add_u64 v[230:231], s[54:55], 0, v[180:181]
	global_load_lds_dwordx4 v[228:229], off
	v_lshl_add_u64 v[228:229], s[90:91], 0, v[178:179]
	s_add_i32 m0, s92, 0x2000
	s_nop 0
	global_load_lds_dwordx4 v[228:229], off
	v_lshl_add_u64 v[228:229], s[54:55], 0, v[184:185]
	s_mov_b32 m0, s56
	s_nop 0
	global_load_lds_dwordx4 v[228:229], off
	s_mov_b32 m0, s57
	s_nop 0
	global_load_lds_dwordx4 v[230:231], off
	ds_read_b128 v[162:165], v210 offset:16384
	ds_read_b128 v[166:169], v210 offset:17408
	ds_read_b128 v[170:173], v210 offset:18432
	ds_read_b128 v[174:177], v210 offset:19456
	ds_read_b128 v[200:203], v210 offset:20480
	ds_read_b128 v[212:215], v210 offset:21504
	ds_read_b128 v[216:219], v210 offset:22528
	ds_read_b128 v[224:227], v210 offset:23552
	s_waitcnt vmcnt(8)
	s_waitcnt lgkmcnt(0)
	s_setprio 1
	s_barrier
	v_mfma_f32_16x16x32_bf16 v[62:65], v[130:133], v[162:165], v[62:65]
	v_mfma_f32_16x16x32_bf16 v[58:61], v[138:141], v[162:165], v[58:61]
	v_mfma_f32_16x16x32_bf16 v[50:53], v[130:133], v[170:173], v[50:53]
	v_mfma_f32_16x16x32_bf16 v[42:45], v[138:141], v[170:173], v[42:45]
	v_mfma_f32_16x16x32_bf16 v[34:37], v[130:133], v[200:203], v[34:37]
	v_mfma_f32_16x16x32_bf16 v[26:29], v[138:141], v[200:203], v[26:29]
	v_mfma_f32_16x16x32_bf16 v[18:21], v[130:133], v[216:219], v[18:21]
	v_mfma_f32_16x16x32_bf16 v[10:13], v[138:141], v[216:219], v[10:13]
	v_mfma_f32_16x16x32_bf16 v[62:65], v[134:137], v[166:169], v[62:65]
	v_mfma_f32_16x16x32_bf16 v[58:61], v[142:145], v[166:169], v[58:61]
	v_mfma_f32_16x16x32_bf16 v[50:53], v[134:137], v[174:177], v[50:53]
	v_mfma_f32_16x16x32_bf16 v[42:45], v[142:145], v[174:177], v[42:45]
	v_mfma_f32_16x16x32_bf16 v[34:37], v[134:137], v[212:215], v[34:37]
	v_mfma_f32_16x16x32_bf16 v[26:29], v[142:145], v[212:215], v[26:29]
	v_mfma_f32_16x16x32_bf16 v[18:21], v[134:137], v[224:227], v[18:21]
	v_mfma_f32_16x16x32_bf16 v[10:13], v[142:145], v[224:227], v[10:13]
	v_mfma_f32_16x16x32_bf16 v[54:57], v[146:149], v[162:165], v[54:57]
	v_mfma_f32_16x16x32_bf16 v[46:49], v[154:157], v[162:165], v[46:49]
	v_mfma_f32_16x16x32_bf16 v[38:41], v[146:149], v[170:173], v[38:41]
	v_mfma_f32_16x16x32_bf16 v[30:33], v[154:157], v[170:173], v[30:33]
	v_mfma_f32_16x16x32_bf16 v[22:25], v[146:149], v[200:203], v[22:25]
	v_mfma_f32_16x16x32_bf16 v[14:17], v[154:157], v[200:203], v[14:17]
	v_mfma_f32_16x16x32_bf16 v[6:9], v[146:149], v[216:219], v[6:9]
	v_mfma_f32_16x16x32_bf16 v[2:5], v[154:157], v[216:219], v[2:5]
	v_mfma_f32_16x16x32_bf16 v[54:57], v[150:153], v[166:169], v[54:57]
	v_mfma_f32_16x16x32_bf16 v[46:49], v[158:161], v[166:169], v[46:49]
	v_mfma_f32_16x16x32_bf16 v[38:41], v[150:153], v[174:177], v[38:41]
	v_mfma_f32_16x16x32_bf16 v[30:33], v[158:161], v[174:177], v[30:33]
	v_mfma_f32_16x16x32_bf16 v[22:25], v[150:153], v[212:215], v[22:25]
	v_mfma_f32_16x16x32_bf16 v[14:17], v[158:161], v[212:215], v[14:17]
	v_mfma_f32_16x16x32_bf16 v[6:9], v[150:153], v[224:227], v[6:9]
	v_mfma_f32_16x16x32_bf16 v[2:5], v[158:161], v[224:227], v[2:5]
	s_barrier
	s_setprio 0
	s_add_i32 s90, 0, 0x18000
	s_add_i32 s91, 0, 0x1c000
	v_add_u32_e32 v142, s90, v189
	v_add_u32_e32 v158, s91, v189
	s_add_u32 s54, s54, 0x100000
	s_addc_u32 s55, s55, 0
	s_mov_b32 m0, s58
	v_lshl_add_u64 v[232:233], s[54:55], 0, v[184:185]
	global_load_lds_dwordx4 v[232:233], off
	v_lshl_add_u64 v[232:233], s[54:55], 0, v[180:181]
	s_mov_b32 m0, s59
	s_nop 0
	global_load_lds_dwordx4 v[232:233], off
	ds_read_b128 v[130:133], v142
	ds_read_b128 v[134:137], v142 offset:1024
	ds_read_b128 v[138:141], v142 offset:2048
	ds_read_b128 v[142:145], v142 offset:3072
	ds_read_b128 v[146:149], v158
	ds_read_b128 v[150:153], v158 offset:1024
	ds_read_b128 v[154:157], v158 offset:2048
	ds_read_b128 v[158:161], v158 offset:3072
	ds_read_b128 v[162:165], v210 offset:32768
	ds_read_b128 v[166:169], v210 offset:33792
	ds_read_b128 v[170:173], v210 offset:34816
	ds_read_b128 v[174:177], v210 offset:35840
	ds_read_b128 v[200:203], v210 offset:36864
	ds_read_b128 v[212:215], v210 offset:37888
	ds_read_b128 v[216:219], v210 offset:38912
	ds_read_b128 v[224:227], v210 offset:39936
	s_waitcnt vmcnt(8)
	s_waitcnt lgkmcnt(0)
	s_setprio 1
	s_barrier
	v_mfma_f32_16x16x32_bf16 v[126:129], v[130:133], v[162:165], v[126:129]
	v_mfma_f32_16x16x32_bf16 v[122:125], v[138:141], v[162:165], v[122:125]
	v_mfma_f32_16x16x32_bf16 v[110:113], v[130:133], v[170:173], v[110:113]
	v_mfma_f32_16x16x32_bf16 v[106:109], v[138:141], v[170:173], v[106:109]
	v_mfma_f32_16x16x32_bf16 v[94:97], v[130:133], v[200:203], v[94:97]
	v_mfma_f32_16x16x32_bf16 v[90:93], v[138:141], v[200:203], v[90:93]
	v_mfma_f32_16x16x32_bf16 v[78:81], v[130:133], v[216:219], v[78:81]
	v_mfma_f32_16x16x32_bf16 v[74:77], v[138:141], v[216:219], v[74:77]
	v_mfma_f32_16x16x32_bf16 v[126:129], v[134:137], v[166:169], v[126:129]
	v_mfma_f32_16x16x32_bf16 v[122:125], v[142:145], v[166:169], v[122:125]
	v_mfma_f32_16x16x32_bf16 v[110:113], v[134:137], v[174:177], v[110:113]
	v_mfma_f32_16x16x32_bf16 v[106:109], v[142:145], v[174:177], v[106:109]
	v_mfma_f32_16x16x32_bf16 v[94:97], v[134:137], v[212:215], v[94:97]
	v_mfma_f32_16x16x32_bf16 v[90:93], v[142:145], v[212:215], v[90:93]
	v_mfma_f32_16x16x32_bf16 v[78:81], v[134:137], v[224:227], v[78:81]
	v_mfma_f32_16x16x32_bf16 v[74:77], v[142:145], v[224:227], v[74:77]
	v_mfma_f32_16x16x32_bf16 v[118:121], v[146:149], v[162:165], v[118:121]
	v_mfma_f32_16x16x32_bf16 v[114:117], v[154:157], v[162:165], v[114:117]
	v_mfma_f32_16x16x32_bf16 v[102:105], v[146:149], v[170:173], v[102:105]
	v_mfma_f32_16x16x32_bf16 v[98:101], v[154:157], v[170:173], v[98:101]
	v_mfma_f32_16x16x32_bf16 v[86:89], v[146:149], v[200:203], v[86:89]
	v_mfma_f32_16x16x32_bf16 v[82:85], v[154:157], v[200:203], v[82:85]
	v_mfma_f32_16x16x32_bf16 v[70:73], v[146:149], v[216:219], v[70:73]
	v_mfma_f32_16x16x32_bf16 v[66:69], v[154:157], v[216:219], v[66:69]
	v_mfma_f32_16x16x32_bf16 v[118:121], v[150:153], v[166:169], v[118:121]
	v_mfma_f32_16x16x32_bf16 v[114:117], v[158:161], v[166:169], v[114:117]
	v_mfma_f32_16x16x32_bf16 v[102:105], v[150:153], v[174:177], v[102:105]
	v_mfma_f32_16x16x32_bf16 v[98:101], v[158:161], v[174:177], v[98:101]
	v_mfma_f32_16x16x32_bf16 v[86:89], v[150:153], v[212:215], v[86:89]
	v_mfma_f32_16x16x32_bf16 v[82:85], v[158:161], v[212:215], v[82:85]
	v_mfma_f32_16x16x32_bf16 v[70:73], v[150:153], v[224:227], v[70:73]
	v_mfma_f32_16x16x32_bf16 v[66:69], v[158:161], v[224:227], v[66:69]
	s_barrier
	s_setprio 0
	s_add_i32 s54, s90, s31
	v_lshl_add_u64 v[204:205], v[204:205], 0, s[8:9]
	s_mov_b32 m0, s54
	s_nop 0
	global_load_lds_dwordx4 v[204:205], off
	s_add_i32 m0, s54, 0x2000
	s_add_u32 s52, s52, 0x100080
	v_lshl_add_u64 v[204:205], v[220:221], 0, s[8:9]
	s_addc_u32 s53, s53, 0
	s_add_i32 s54, s91, s31
	global_load_lds_dwordx4 v[204:205], off
	v_lshl_add_u64 v[204:205], s[52:53], 0, v[182:183]
	s_mov_b32 m0, s54
	s_nop 0
	global_load_lds_dwordx4 v[204:205], off
	v_lshl_add_u64 v[204:205], s[52:53], 0, v[178:179]
	s_add_i32 m0, s54, 0x2000
	s_nop 0
	global_load_lds_dwordx4 v[204:205], off
	v_lshl_add_u64 v[204:205], v[228:229], 0, s[8:9]
	s_mov_b32 m0, s62
	s_nop 0
	global_load_lds_dwordx4 v[204:205], off
	v_lshl_add_u64 v[204:205], v[230:231], 0, s[8:9]
	s_mov_b32 m0, s63
	s_nop 0
	global_load_lds_dwordx4 v[204:205], off
	ds_read_b128 v[162:165], v210 offset:49152
	ds_read_b128 v[166:169], v210 offset:50176
	ds_read_b128 v[170:173], v210 offset:51200
	ds_read_b128 v[174:177], v210 offset:52224
	ds_read_b128 v[200:203], v210 offset:53248
	ds_read_b128 v[212:215], v210 offset:54272
	ds_read_b128 v[216:219], v210 offset:55296
	ds_read_b128 v[224:227], v210 offset:56320
	s_waitcnt vmcnt(8)
	s_waitcnt lgkmcnt(0)
	s_setprio 1
	s_barrier
	v_mfma_f32_16x16x32_bf16 v[62:65], v[130:133], v[162:165], v[62:65]
	v_mfma_f32_16x16x32_bf16 v[58:61], v[138:141], v[162:165], v[58:61]
	v_mfma_f32_16x16x32_bf16 v[50:53], v[130:133], v[170:173], v[50:53]
	v_mfma_f32_16x16x32_bf16 v[42:45], v[138:141], v[170:173], v[42:45]
	v_mfma_f32_16x16x32_bf16 v[34:37], v[130:133], v[200:203], v[34:37]
	v_mfma_f32_16x16x32_bf16 v[26:29], v[138:141], v[200:203], v[26:29]
	v_mfma_f32_16x16x32_bf16 v[18:21], v[130:133], v[216:219], v[18:21]
	v_mfma_f32_16x16x32_bf16 v[10:13], v[138:141], v[216:219], v[10:13]
	v_mfma_f32_16x16x32_bf16 v[62:65], v[134:137], v[166:169], v[62:65]
	v_mfma_f32_16x16x32_bf16 v[58:61], v[142:145], v[166:169], v[58:61]
	v_mfma_f32_16x16x32_bf16 v[50:53], v[134:137], v[174:177], v[50:53]
	v_mfma_f32_16x16x32_bf16 v[42:45], v[142:145], v[174:177], v[42:45]
	v_mfma_f32_16x16x32_bf16 v[34:37], v[134:137], v[212:215], v[34:37]
	v_mfma_f32_16x16x32_bf16 v[26:29], v[142:145], v[212:215], v[26:29]
	v_mfma_f32_16x16x32_bf16 v[18:21], v[134:137], v[224:227], v[18:21]
	v_mfma_f32_16x16x32_bf16 v[10:13], v[142:145], v[224:227], v[10:13]
	v_mfma_f32_16x16x32_bf16 v[54:57], v[146:149], v[162:165], v[54:57]
	v_mfma_f32_16x16x32_bf16 v[46:49], v[154:157], v[162:165], v[46:49]
	v_mfma_f32_16x16x32_bf16 v[38:41], v[146:149], v[170:173], v[38:41]
	v_mfma_f32_16x16x32_bf16 v[30:33], v[154:157], v[170:173], v[30:33]
	v_mfma_f32_16x16x32_bf16 v[22:25], v[146:149], v[200:203], v[22:25]
	v_mfma_f32_16x16x32_bf16 v[14:17], v[154:157], v[200:203], v[14:17]
	v_mfma_f32_16x16x32_bf16 v[6:9], v[146:149], v[216:219], v[6:9]
	v_mfma_f32_16x16x32_bf16 v[2:5], v[154:157], v[216:219], v[2:5]
	v_mfma_f32_16x16x32_bf16 v[54:57], v[150:153], v[166:169], v[54:57]
	v_mfma_f32_16x16x32_bf16 v[46:49], v[158:161], v[166:169], v[46:49]
	v_mfma_f32_16x16x32_bf16 v[38:41], v[150:153], v[174:177], v[38:41]
	v_mfma_f32_16x16x32_bf16 v[30:33], v[158:161], v[174:177], v[30:33]
	v_mfma_f32_16x16x32_bf16 v[22:25], v[150:153], v[212:215], v[22:25]
	v_mfma_f32_16x16x32_bf16 v[14:17], v[158:161], v[212:215], v[14:17]
	v_mfma_f32_16x16x32_bf16 v[6:9], v[150:153], v[224:227], v[6:9]
	v_mfma_f32_16x16x32_bf16 v[2:5], v[158:161], v[224:227], v[2:5]
	s_barrier
	s_setprio 0
	s_add_i32 s89, s89, 2
	s_add_u32 s50, s50, 0x100
	s_addc_u32 s51, s51, 0
	s_add_u32 s87, s87, 0x100
	s_addc_u32 s88, s88, 0
	s_cmp_gt_u32 s89, 61
	s_cbranch_scc0 .LBB0_224
	s_and_b64 vcc, exec, s[10:11]
	s_cbranch_vccz .LBB0_229
	s_barrier
	v_lshl_add_u32 v200, s0, 8, v1
	s_cmp_gt_i32 s84, 15
	s_mov_b64 s[50:51], -1
	s_cbranch_scc1 .LBB0_230

.Lpeelb:
	v_add_u32_e32 v142, s51, v220
	v_add_u32_e32 v158, s81, v220
	s_add_u32 s16, s0, 0xfff00080
	s_addc_u32 s17, s1, -1
	s_cmp_eq_u32 s26, 60
	s_cselect_b32 s19, s20, s17
	s_cselect_b32 s18, s21, s16
	s_cselect_b32 s17, s22, s25
	s_cselect_b32 s16, s23, s24
	v_lshl_add_u64 v[218:219], s[0:1], 0, v[194:195]
	s_add_i32 m0, s31, 0xc000
	s_nop 0
	global_load_lds_dwordx4 v[218:219], off
	v_lshl_add_u64 v[218:219], s[0:1], 0, v[196:197]
	s_add_i32 m0, s31, 0xe000
	s_nop 0
	global_load_lds_dwordx4 v[218:219], off
	ds_read_b128 v[130:133], v142
	ds_read_b128 v[134:137], v142 offset:1024
	ds_read_b128 v[138:141], v142 offset:2048
	ds_read_b128 v[142:145], v142 offset:3072
	ds_read_b128 v[146:149], v158
	ds_read_b128 v[150:153], v158 offset:1024
	ds_read_b128 v[154:157], v158 offset:2048
	ds_read_b128 v[158:161], v158 offset:3072
	ds_read_b128 v[162:165], v233
	ds_read_b128 v[166:169], v233 offset:1024
	ds_read_b128 v[170:173], v233 offset:2048
	ds_read_b128 v[174:177], v233 offset:3072
	ds_read_b128 v[202:205], v233 offset:4096
	ds_read_b128 v[206:209], v233 offset:5120
	ds_read_b128 v[210:213], v233 offset:6144
	ds_read_b128 v[214:217], v233 offset:7168
	s_waitcnt vmcnt(8)
	s_waitcnt lgkmcnt(0)
	s_setprio 1
	s_barrier
	v_mfma_f32_16x16x32_bf16 v[90:93], v[130:133], v[162:165], 0
	v_mfma_f32_16x16x32_bf16 v[58:61], v[138:141], v[162:165], 0
	v_mfma_f32_16x16x32_bf16 v[98:101], v[130:133], v[170:173], 0
	v_mfma_f32_16x16x32_bf16 v[66:69], v[138:141], v[170:173], 0
	v_mfma_f32_16x16x32_bf16 v[102:105], v[130:133], v[202:205], 0
	v_mfma_f32_16x16x32_bf16 v[70:73], v[138:141], v[202:205], 0
	v_mfma_f32_16x16x32_bf16 v[110:113], v[130:133], v[210:213], 0
	v_mfma_f32_16x16x32_bf16 v[78:81], v[138:141], v[210:213], 0
	v_mfma_f32_16x16x32_bf16 v[90:93], v[134:137], v[166:169], v[90:93]
	v_mfma_f32_16x16x32_bf16 v[58:61], v[142:145], v[166:169], v[58:61]
	v_mfma_f32_16x16x32_bf16 v[98:101], v[134:137], v[174:177], v[98:101]
	v_mfma_f32_16x16x32_bf16 v[66:69], v[142:145], v[174:177], v[66:69]
	v_mfma_f32_16x16x32_bf16 v[102:105], v[134:137], v[206:209], v[102:105]
	v_mfma_f32_16x16x32_bf16 v[70:73], v[142:145], v[206:209], v[70:73]
	v_mfma_f32_16x16x32_bf16 v[110:113], v[134:137], v[214:217], v[110:113]
	v_mfma_f32_16x16x32_bf16 v[78:81], v[142:145], v[214:217], v[78:81]
	v_mfma_f32_16x16x32_bf16 v[26:29], v[146:149], v[162:165], 0
	v_mfma_f32_16x16x32_bf16 v[2:5], v[154:157], v[162:165], 0
	v_mfma_f32_16x16x32_bf16 v[34:37], v[146:149], v[170:173], 0
	v_mfma_f32_16x16x32_bf16 v[6:9], v[154:157], v[170:173], 0
	v_mfma_f32_16x16x32_bf16 v[38:41], v[146:149], v[202:205], 0
	v_mfma_f32_16x16x32_bf16 v[10:13], v[154:157], v[202:205], 0
	v_mfma_f32_16x16x32_bf16 v[46:49], v[146:149], v[210:213], 0
	v_mfma_f32_16x16x32_bf16 v[14:17], v[154:157], v[210:213], 0
	v_mfma_f32_16x16x32_bf16 v[26:29], v[150:153], v[166:169], v[26:29]
	v_mfma_f32_16x16x32_bf16 v[2:5], v[158:161], v[166:169], v[2:5]
	v_mfma_f32_16x16x32_bf16 v[34:37], v[150:153], v[174:177], v[34:37]
	v_mfma_f32_16x16x32_bf16 v[6:9], v[158:161], v[174:177], v[6:9]
	v_mfma_f32_16x16x32_bf16 v[38:41], v[150:153], v[206:209], v[38:41]
	v_mfma_f32_16x16x32_bf16 v[10:13], v[158:161], v[206:209], v[10:13]
	v_mfma_f32_16x16x32_bf16 v[46:49], v[150:153], v[214:217], v[46:49]
	v_mfma_f32_16x16x32_bf16 v[14:17], v[158:161], v[214:217], v[14:17]
	s_barrier
	s_setprio 0
	s_add_i32 s27, s51, s15
	v_lshl_add_u64 v[218:219], s[16:17], 0, v[178:179]
	s_mov_b32 m0, s27
	s_nop 0
	global_load_lds_dwordx4 v[218:219], off
	s_add_i32 m0, s27, 0x2000
	s_add_u32 s62, s16, 0x100000
	v_lshl_add_u64 v[242:243], s[16:17], 0, v[180:181]
	s_addc_u32 s63, s17, 0
	s_add_i32 s27, s81, s15
	global_load_lds_dwordx4 v[242:243], off
	v_lshl_add_u64 v[244:245], s[62:63], 0, v[178:179]
	s_mov_b32 m0, s27
	v_lshl_add_u64 v[246:247], s[18:19], 0, v[180:181]
	global_load_lds_dwordx4 v[244:245], off
	v_lshl_add_u64 v[244:245], s[62:63], 0, v[180:181]
	s_add_i32 m0, s27, 0x2000
	s_nop 0
	global_load_lds_dwordx4 v[244:245], off
	v_lshl_add_u64 v[244:245], s[18:19], 0, v[178:179]
	s_mov_b32 m0, s31
	s_nop 0
	global_load_lds_dwordx4 v[244:245], off
	s_mov_b32 m0, s34
	s_nop 0
	global_load_lds_dwordx4 v[246:247], off
	ds_read_b128 v[162:165], v233 offset:16384
	ds_read_b128 v[166:169], v233 offset:17408
	ds_read_b128 v[170:173], v233 offset:18432
	ds_read_b128 v[174:177], v233 offset:19456
	ds_read_b128 v[202:205], v233 offset:20480
	ds_read_b128 v[206:209], v233 offset:21504
	ds_read_b128 v[210:213], v233 offset:22528
	ds_read_b128 v[214:217], v233 offset:23552
	s_waitcnt vmcnt(8)
	s_waitcnt lgkmcnt(0)
	s_setprio 1
	s_barrier
	v_mfma_f32_16x16x32_bf16 v[114:117], v[130:133], v[162:165], 0
	v_mfma_f32_16x16x32_bf16 v[82:85], v[138:141], v[162:165], 0
	v_mfma_f32_16x16x32_bf16 v[118:121], v[130:133], v[170:173], 0
	v_mfma_f32_16x16x32_bf16 v[86:89], v[138:141], v[170:173], 0
	v_mfma_f32_16x16x32_bf16 v[122:125], v[130:133], v[202:205], 0
	v_mfma_f32_16x16x32_bf16 v[94:97], v[138:141], v[202:205], 0
	v_mfma_f32_16x16x32_bf16 v[126:129], v[130:133], v[210:213], 0
	v_mfma_f32_16x16x32_bf16 v[106:109], v[138:141], v[210:213], 0
	v_mfma_f32_16x16x32_bf16 v[114:117], v[134:137], v[166:169], v[114:117]
	v_mfma_f32_16x16x32_bf16 v[82:85], v[142:145], v[166:169], v[82:85]
	v_mfma_f32_16x16x32_bf16 v[118:121], v[134:137], v[174:177], v[118:121]
	v_mfma_f32_16x16x32_bf16 v[86:89], v[142:145], v[174:177], v[86:89]
	v_mfma_f32_16x16x32_bf16 v[122:125], v[134:137], v[206:209], v[122:125]
	v_mfma_f32_16x16x32_bf16 v[94:97], v[142:145], v[206:209], v[94:97]
	v_mfma_f32_16x16x32_bf16 v[126:129], v[134:137], v[214:217], v[126:129]
	v_mfma_f32_16x16x32_bf16 v[106:109], v[142:145], v[214:217], v[106:109]
	v_mfma_f32_16x16x32_bf16 v[50:53], v[146:149], v[162:165], 0
	v_mfma_f32_16x16x32_bf16 v[18:21], v[154:157], v[162:165], 0
	v_mfma_f32_16x16x32_bf16 v[54:57], v[146:149], v[170:173], 0
	v_mfma_f32_16x16x32_bf16 v[22:25], v[154:157], v[170:173], 0
	v_mfma_f32_16x16x32_bf16 v[62:65], v[146:149], v[202:205], 0
	v_mfma_f32_16x16x32_bf16 v[30:33], v[154:157], v[202:205], 0
	v_mfma_f32_16x16x32_bf16 v[74:77], v[146:149], v[210:213], 0
	v_mfma_f32_16x16x32_bf16 v[42:45], v[154:157], v[210:213], 0
	v_mfma_f32_16x16x32_bf16 v[50:53], v[150:153], v[166:169], v[50:53]
	v_mfma_f32_16x16x32_bf16 v[18:21], v[158:161], v[166:169], v[18:21]
	v_mfma_f32_16x16x32_bf16 v[54:57], v[150:153], v[174:177], v[54:57]
	v_mfma_f32_16x16x32_bf16 v[22:25], v[158:161], v[174:177], v[22:25]
	v_mfma_f32_16x16x32_bf16 v[62:65], v[150:153], v[206:209], v[62:65]
	v_mfma_f32_16x16x32_bf16 v[30:33], v[158:161], v[206:209], v[30:33]
	v_mfma_f32_16x16x32_bf16 v[74:77], v[150:153], v[214:217], v[74:77]
	v_mfma_f32_16x16x32_bf16 v[42:45], v[158:161], v[214:217], v[42:45]
	s_barrier
	s_setprio 0
	s_add_i32 s27, 0, 0x18000
	s_add_i32 s59, 0, 0x1c000
	v_add_u32_e32 v142, s27, v220
	v_add_u32_e32 v158, s59, v220
	s_add_u32 s18, s18, 0x100000
	s_addc_u32 s19, s19, 0
	s_mov_b32 m0, s35
	v_lshl_add_u64 v[248:249], s[18:19], 0, v[178:179]
	global_load_lds_dwordx4 v[248:249], off
	v_lshl_add_u64 v[248:249], s[18:19], 0, v[180:181]
	s_mov_b32 m0, s86
	s_nop 0
	global_load_lds_dwordx4 v[248:249], off
	ds_read_b128 v[130:133], v142
	ds_read_b128 v[134:137], v142 offset:1024
	ds_read_b128 v[138:141], v142 offset:2048
	ds_read_b128 v[142:145], v142 offset:3072
	ds_read_b128 v[146:149], v158
	ds_read_b128 v[150:153], v158 offset:1024
	ds_read_b128 v[154:157], v158 offset:2048
	ds_read_b128 v[158:161], v158 offset:3072
	ds_read_b128 v[162:165], v233 offset:32768
	ds_read_b128 v[166:169], v233 offset:33792
	ds_read_b128 v[170:173], v233 offset:34816
	ds_read_b128 v[174:177], v233 offset:35840
	ds_read_b128 v[202:205], v233 offset:36864
	ds_read_b128 v[206:209], v233 offset:37888
	ds_read_b128 v[210:213], v233 offset:38912
	ds_read_b128 v[214:217], v233 offset:39936
	s_waitcnt vmcnt(8)
	s_waitcnt lgkmcnt(0)
	s_setprio 1
	s_barrier
	v_mfma_f32_16x16x32_bf16 v[90:93], v[130:133], v[162:165], v[90:93]
	v_mfma_f32_16x16x32_bf16 v[58:61], v[138:141], v[162:165], v[58:61]
	v_mfma_f32_16x16x32_bf16 v[98:101], v[130:133], v[170:173], v[98:101]
	v_mfma_f32_16x16x32_bf16 v[66:69], v[138:141], v[170:173], v[66:69]
	v_mfma_f32_16x16x32_bf16 v[102:105], v[130:133], v[202:205], v[102:105]
	v_mfma_f32_16x16x32_bf16 v[70:73], v[138:141], v[202:205], v[70:73]
	v_mfma_f32_16x16x32_bf16 v[110:113], v[130:133], v[210:213], v[110:113]
	v_mfma_f32_16x16x32_bf16 v[78:81], v[138:141], v[210:213], v[78:81]
	v_mfma_f32_16x16x32_bf16 v[90:93], v[134:137], v[166:169], v[90:93]
	v_mfma_f32_16x16x32_bf16 v[58:61], v[142:145], v[166:169], v[58:61]
	v_mfma_f32_16x16x32_bf16 v[98:101], v[134:137], v[174:177], v[98:101]
	v_mfma_f32_16x16x32_bf16 v[66:69], v[142:145], v[174:177], v[66:69]
	v_mfma_f32_16x16x32_bf16 v[102:105], v[134:137], v[206:209], v[102:105]
	v_mfma_f32_16x16x32_bf16 v[70:73], v[142:145], v[206:209], v[70:73]
	v_mfma_f32_16x16x32_bf16 v[110:113], v[134:137], v[214:217], v[110:113]
	v_mfma_f32_16x16x32_bf16 v[78:81], v[142:145], v[214:217], v[78:81]
	v_mfma_f32_16x16x32_bf16 v[26:29], v[146:149], v[162:165], v[26:29]
	v_mfma_f32_16x16x32_bf16 v[2:5], v[154:157], v[162:165], v[2:5]
	v_mfma_f32_16x16x32_bf16 v[34:37], v[146:149], v[170:173], v[34:37]
	v_mfma_f32_16x16x32_bf16 v[6:9], v[154:157], v[170:173], v[6:9]
	v_mfma_f32_16x16x32_bf16 v[38:41], v[146:149], v[202:205], v[38:41]
	v_mfma_f32_16x16x32_bf16 v[10:13], v[154:157], v[202:205], v[10:13]
	v_mfma_f32_16x16x32_bf16 v[46:49], v[146:149], v[210:213], v[46:49]
	v_mfma_f32_16x16x32_bf16 v[14:17], v[154:157], v[210:213], v[14:17]
	v_mfma_f32_16x16x32_bf16 v[26:29], v[150:153], v[166:169], v[26:29]
	v_mfma_f32_16x16x32_bf16 v[2:5], v[158:161], v[166:169], v[2:5]
	v_mfma_f32_16x16x32_bf16 v[34:37], v[150:153], v[174:177], v[34:37]
	v_mfma_f32_16x16x32_bf16 v[6:9], v[158:161], v[174:177], v[6:9]
	v_mfma_f32_16x16x32_bf16 v[38:41], v[150:153], v[206:209], v[38:41]
	v_mfma_f32_16x16x32_bf16 v[10:13], v[158:161], v[206:209], v[10:13]
	v_mfma_f32_16x16x32_bf16 v[46:49], v[150:153], v[214:217], v[46:49]
	v_mfma_f32_16x16x32_bf16 v[14:17], v[158:161], v[214:217], v[14:17]
	s_barrier
	s_setprio 0
	s_add_i32 s18, s27, s15
	v_lshl_add_u64 v[218:219], v[218:219], 0, s[44:45]
	s_mov_b32 m0, s18
	s_nop 0
	global_load_lds_dwordx4 v[218:219], off
	s_add_i32 m0, s18, 0x2000
	s_add_u32 s16, s16, 0x100080
	v_lshl_add_u64 v[218:219], v[242:243], 0, s[44:45]
	s_addc_u32 s17, s17, 0
	s_add_i32 s18, s59, s15
	global_load_lds_dwordx4 v[218:219], off
	v_lshl_add_u64 v[218:219], s[16:17], 0, v[178:179]
	s_mov_b32 m0, s18
	s_nop 0
	global_load_lds_dwordx4 v[218:219], off
	v_lshl_add_u64 v[218:219], s[16:17], 0, v[180:181]
	s_add_i32 m0, s18, 0x2000
	s_nop 0
	global_load_lds_dwordx4 v[218:219], off
	v_lshl_add_u64 v[218:219], v[244:245], 0, s[44:45]
	s_mov_b32 m0, s66
	s_nop 0
	global_load_lds_dwordx4 v[218:219], off
	v_lshl_add_u64 v[218:219], v[246:247], 0, s[44:45]
	s_mov_b32 m0, s67
	s_nop 0
	global_load_lds_dwordx4 v[218:219], off
	ds_read_b128 v[162:165], v233 offset:49152
	ds_read_b128 v[166:169], v233 offset:50176
	ds_read_b128 v[170:173], v233 offset:51200
	ds_read_b128 v[174:177], v233 offset:52224
	ds_read_b128 v[202:205], v233 offset:53248
	ds_read_b128 v[206:209], v233 offset:54272
	ds_read_b128 v[210:213], v233 offset:55296
	ds_read_b128 v[214:217], v233 offset:56320
	s_waitcnt vmcnt(8)
	s_waitcnt lgkmcnt(0)
	s_setprio 1
	s_barrier
	v_mfma_f32_16x16x32_bf16 v[114:117], v[130:133], v[162:165], v[114:117]
	v_mfma_f32_16x16x32_bf16 v[82:85], v[138:141], v[162:165], v[82:85]
	v_mfma_f32_16x16x32_bf16 v[118:121], v[130:133], v[170:173], v[118:121]
	v_mfma_f32_16x16x32_bf16 v[86:89], v[138:141], v[170:173], v[86:89]
	v_mfma_f32_16x16x32_bf16 v[122:125], v[130:133], v[202:205], v[122:125]
	v_mfma_f32_16x16x32_bf16 v[94:97], v[138:141], v[202:205], v[94:97]
	v_mfma_f32_16x16x32_bf16 v[126:129], v[130:133], v[210:213], v[126:129]
	v_mfma_f32_16x16x32_bf16 v[106:109], v[138:141], v[210:213], v[106:109]
	v_mfma_f32_16x16x32_bf16 v[114:117], v[134:137], v[166:169], v[114:117]
	v_mfma_f32_16x16x32_bf16 v[82:85], v[142:145], v[166:169], v[82:85]
	v_mfma_f32_16x16x32_bf16 v[118:121], v[134:137], v[174:177], v[118:121]
	v_mfma_f32_16x16x32_bf16 v[86:89], v[142:145], v[174:177], v[86:89]
	v_mfma_f32_16x16x32_bf16 v[122:125], v[134:137], v[206:209], v[122:125]
	v_mfma_f32_16x16x32_bf16 v[94:97], v[142:145], v[206:209], v[94:97]
	v_mfma_f32_16x16x32_bf16 v[126:129], v[134:137], v[214:217], v[126:129]
	v_mfma_f32_16x16x32_bf16 v[106:109], v[142:145], v[214:217], v[106:109]
	v_mfma_f32_16x16x32_bf16 v[50:53], v[146:149], v[162:165], v[50:53]
	v_mfma_f32_16x16x32_bf16 v[18:21], v[154:157], v[162:165], v[18:21]
	v_mfma_f32_16x16x32_bf16 v[54:57], v[146:149], v[170:173], v[54:57]
	v_mfma_f32_16x16x32_bf16 v[22:25], v[154:157], v[170:173], v[22:25]
	v_mfma_f32_16x16x32_bf16 v[62:65], v[146:149], v[202:205], v[62:65]
	v_mfma_f32_16x16x32_bf16 v[30:33], v[154:157], v[202:205], v[30:33]
	v_mfma_f32_16x16x32_bf16 v[74:77], v[146:149], v[210:213], v[74:77]
	v_mfma_f32_16x16x32_bf16 v[42:45], v[154:157], v[210:213], v[42:45]
	v_mfma_f32_16x16x32_bf16 v[50:53], v[150:153], v[166:169], v[50:53]
	v_mfma_f32_16x16x32_bf16 v[18:21], v[158:161], v[166:169], v[18:21]
	v_mfma_f32_16x16x32_bf16 v[54:57], v[150:153], v[174:177], v[54:57]
	v_mfma_f32_16x16x32_bf16 v[22:25], v[158:161], v[174:177], v[22:25]
	v_mfma_f32_16x16x32_bf16 v[62:65], v[150:153], v[206:209], v[62:65]
	v_mfma_f32_16x16x32_bf16 v[30:33], v[158:161], v[206:209], v[30:33]
	v_mfma_f32_16x16x32_bf16 v[74:77], v[150:153], v[214:217], v[74:77]
	v_mfma_f32_16x16x32_bf16 v[42:45], v[158:161], v[214:217], v[42:45]
	s_barrier
	s_setprio 0
	s_add_i32 s26, s26, 2
	s_add_u32 s0, s0, 0x100
	s_addc_u32 s1, s1, 0
	s_add_u32 s24, s24, 0x100
	s_addc_u32 s25, s25, 0
.LBB0_672:
	v_add_u32_e32 v142, s51, v220
	v_add_u32_e32 v158, s81, v220
	s_add_u32 s16, s0, 0xfff00080
	s_addc_u32 s17, s1, -1
	s_cmp_eq_u32 s26, 60
	s_cselect_b32 s19, s20, s17
	s_cselect_b32 s18, s21, s16
	s_cselect_b32 s17, s22, s25
	s_cselect_b32 s16, s23, s24
	v_lshl_add_u64 v[218:219], s[0:1], 0, v[194:195]
	s_add_i32 m0, s31, 0xc000
	s_nop 0
	global_load_lds_dwordx4 v[218:219], off
	v_lshl_add_u64 v[218:219], s[0:1], 0, v[196:197]
	s_add_i32 m0, s31, 0xe000
	s_nop 0
	global_load_lds_dwordx4 v[218:219], off
	ds_read_b128 v[130:133], v142
	ds_read_b128 v[134:137], v142 offset:1024
	ds_read_b128 v[138:141], v142 offset:2048
	ds_read_b128 v[142:145], v142 offset:3072
	ds_read_b128 v[146:149], v158
	ds_read_b128 v[150:153], v158 offset:1024
	ds_read_b128 v[154:157], v158 offset:2048
	ds_read_b128 v[158:161], v158 offset:3072
	ds_read_b128 v[162:165], v233
	ds_read_b128 v[166:169], v233 offset:1024
	ds_read_b128 v[170:173], v233 offset:2048
	ds_read_b128 v[174:177], v233 offset:3072
	ds_read_b128 v[202:205], v233 offset:4096
	ds_read_b128 v[206:209], v233 offset:5120
	ds_read_b128 v[210:213], v233 offset:6144
	ds_read_b128 v[214:217], v233 offset:7168
	s_waitcnt vmcnt(8)
	s_waitcnt lgkmcnt(0)
	s_setprio 1
	s_barrier
	v_mfma_f32_16x16x32_bf16 v[90:93], v[130:133], v[162:165], v[90:93]
	v_mfma_f32_16x16x32_bf16 v[58:61], v[138:141], v[162:165], v[58:61]
	v_mfma_f32_16x16x32_bf16 v[98:101], v[130:133], v[170:173], v[98:101]
	v_mfma_f32_16x16x32_bf16 v[66:69], v[138:141], v[170:173], v[66:69]
	v_mfma_f32_16x16x32_bf16 v[102:105], v[130:133], v[202:205], v[102:105]
	v_mfma_f32_16x16x32_bf16 v[70:73], v[138:141], v[202:205], v[70:73]
	v_mfma_f32_16x16x32_bf16 v[110:113], v[130:133], v[210:213], v[110:113]
	v_mfma_f32_16x16x32_bf16 v[78:81], v[138:141], v[210:213], v[78:81]
	v_mfma_f32_16x16x32_bf16 v[90:93], v[134:137], v[166:169], v[90:93]
	v_mfma_f32_16x16x32_bf16 v[58:61], v[142:145], v[166:169], v[58:61]
	v_mfma_f32_16x16x32_bf16 v[98:101], v[134:137], v[174:177], v[98:101]
	v_mfma_f32_16x16x32_bf16 v[66:69], v[142:145], v[174:177], v[66:69]
	v_mfma_f32_16x16x32_bf16 v[102:105], v[134:137], v[206:209], v[102:105]
	v_mfma_f32_16x16x32_bf16 v[70:73], v[142:145], v[206:209], v[70:73]
	v_mfma_f32_16x16x32_bf16 v[110:113], v[134:137], v[214:217], v[110:113]
	v_mfma_f32_16x16x32_bf16 v[78:81], v[142:145], v[214:217], v[78:81]
	v_mfma_f32_16x16x32_bf16 v[26:29], v[146:149], v[162:165], v[26:29]
	v_mfma_f32_16x16x32_bf16 v[2:5], v[154:157], v[162:165], v[2:5]
	v_mfma_f32_16x16x32_bf16 v[34:37], v[146:149], v[170:173], v[34:37]
	v_mfma_f32_16x16x32_bf16 v[6:9], v[154:157], v[170:173], v[6:9]
	v_mfma_f32_16x16x32_bf16 v[38:41], v[146:149], v[202:205], v[38:41]
	v_mfma_f32_16x16x32_bf16 v[10:13], v[154:157], v[202:205], v[10:13]
	v_mfma_f32_16x16x32_bf16 v[46:49], v[146:149], v[210:213], v[46:49]
	v_mfma_f32_16x16x32_bf16 v[14:17], v[154:157], v[210:213], v[14:17]
	v_mfma_f32_16x16x32_bf16 v[26:29], v[150:153], v[166:169], v[26:29]
	v_mfma_f32_16x16x32_bf16 v[2:5], v[158:161], v[166:169], v[2:5]
	v_mfma_f32_16x16x32_bf16 v[34:37], v[150:153], v[174:177], v[34:37]
	v_mfma_f32_16x16x32_bf16 v[6:9], v[158:161], v[174:177], v[6:9]
	v_mfma_f32_16x16x32_bf16 v[38:41], v[150:153], v[206:209], v[38:41]
	v_mfma_f32_16x16x32_bf16 v[10:13], v[158:161], v[206:209], v[10:13]
	v_mfma_f32_16x16x32_bf16 v[46:49], v[150:153], v[214:217], v[46:49]
	v_mfma_f32_16x16x32_bf16 v[14:17], v[158:161], v[214:217], v[14:17]
	s_barrier
	s_setprio 0
	s_add_i32 s27, s51, s15
	v_lshl_add_u64 v[218:219], s[16:17], 0, v[178:179]
	s_mov_b32 m0, s27
	s_nop 0
	global_load_lds_dwordx4 v[218:219], off
	s_add_i32 m0, s27, 0x2000
	s_add_u32 s62, s16, 0x100000
	v_lshl_add_u64 v[242:243], s[16:17], 0, v[180:181]
	s_addc_u32 s63, s17, 0
	s_add_i32 s27, s81, s15
	global_load_lds_dwordx4 v[242:243], off
	v_lshl_add_u64 v[244:245], s[62:63], 0, v[178:179]
	s_mov_b32 m0, s27
	v_lshl_add_u64 v[246:247], s[18:19], 0, v[180:181]
	global_load_lds_dwordx4 v[244:245], off
	v_lshl_add_u64 v[244:245], s[62:63], 0, v[180:181]
	s_add_i32 m0, s27, 0x2000
	s_nop 0
	global_load_lds_dwordx4 v[244:245], off
	v_lshl_add_u64 v[244:245], s[18:19], 0, v[178:179]
	s_mov_b32 m0, s31
	s_nop 0
	global_load_lds_dwordx4 v[244:245], off
	s_mov_b32 m0, s34
	s_nop 0
	global_load_lds_dwordx4 v[246:247], off
	ds_read_b128 v[162:165], v233 offset:16384
	ds_read_b128 v[166:169], v233 offset:17408
	ds_read_b128 v[170:173], v233 offset:18432
	ds_read_b128 v[174:177], v233 offset:19456
	ds_read_b128 v[202:205], v233 offset:20480
	ds_read_b128 v[206:209], v233 offset:21504
	ds_read_b128 v[210:213], v233 offset:22528
	ds_read_b128 v[214:217], v233 offset:23552
	s_waitcnt vmcnt(8)
	s_waitcnt lgkmcnt(0)
	s_setprio 1
	s_barrier
	v_mfma_f32_16x16x32_bf16 v[114:117], v[130:133], v[162:165], v[114:117]
	v_mfma_f32_16x16x32_bf16 v[82:85], v[138:141], v[162:165], v[82:85]
	v_mfma_f32_16x16x32_bf16 v[118:121], v[130:133], v[170:173], v[118:121]
	v_mfma_f32_16x16x32_bf16 v[86:89], v[138:141], v[170:173], v[86:89]
	v_mfma_f32_16x16x32_bf16 v[122:125], v[130:133], v[202:205], v[122:125]
	v_mfma_f32_16x16x32_bf16 v[94:97], v[138:141], v[202:205], v[94:97]
	v_mfma_f32_16x16x32_bf16 v[126:129], v[130:133], v[210:213], v[126:129]
	v_mfma_f32_16x16x32_bf16 v[106:109], v[138:141], v[210:213], v[106:109]
	v_mfma_f32_16x16x32_bf16 v[114:117], v[134:137], v[166:169], v[114:117]
	v_mfma_f32_16x16x32_bf16 v[82:85], v[142:145], v[166:169], v[82:85]
	v_mfma_f32_16x16x32_bf16 v[118:121], v[134:137], v[174:177], v[118:121]
	v_mfma_f32_16x16x32_bf16 v[86:89], v[142:145], v[174:177], v[86:89]
	v_mfma_f32_16x16x32_bf16 v[122:125], v[134:137], v[206:209], v[122:125]
	v_mfma_f32_16x16x32_bf16 v[94:97], v[142:145], v[206:209], v[94:97]
	v_mfma_f32_16x16x32_bf16 v[126:129], v[134:137], v[214:217], v[126:129]
	v_mfma_f32_16x16x32_bf16 v[106:109], v[142:145], v[214:217], v[106:109]
	v_mfma_f32_16x16x32_bf16 v[50:53], v[146:149], v[162:165], v[50:53]
	v_mfma_f32_16x16x32_bf16 v[18:21], v[154:157], v[162:165], v[18:21]
	v_mfma_f32_16x16x32_bf16 v[54:57], v[146:149], v[170:173], v[54:57]
	v_mfma_f32_16x16x32_bf16 v[22:25], v[154:157], v[170:173], v[22:25]
	v_mfma_f32_16x16x32_bf16 v[62:65], v[146:149], v[202:205], v[62:65]
	v_mfma_f32_16x16x32_bf16 v[30:33], v[154:157], v[202:205], v[30:33]
	v_mfma_f32_16x16x32_bf16 v[74:77], v[146:149], v[210:213], v[74:77]
	v_mfma_f32_16x16x32_bf16 v[42:45], v[154:157], v[210:213], v[42:45]
	v_mfma_f32_16x16x32_bf16 v[50:53], v[150:153], v[166:169], v[50:53]
	v_mfma_f32_16x16x32_bf16 v[18:21], v[158:161], v[166:169], v[18:21]
	v_mfma_f32_16x16x32_bf16 v[54:57], v[150:153], v[174:177], v[54:57]
	v_mfma_f32_16x16x32_bf16 v[22:25], v[158:161], v[174:177], v[22:25]
	v_mfma_f32_16x16x32_bf16 v[62:65], v[150:153], v[206:209], v[62:65]
	v_mfma_f32_16x16x32_bf16 v[30:33], v[158:161], v[206:209], v[30:33]
	v_mfma_f32_16x16x32_bf16 v[74:77], v[150:153], v[214:217], v[74:77]
	v_mfma_f32_16x16x32_bf16 v[42:45], v[158:161], v[214:217], v[42:45]
	s_barrier
	s_setprio 0
	s_add_i32 s27, 0, 0x18000
	s_add_i32 s59, 0, 0x1c000
	v_add_u32_e32 v142, s27, v220
	v_add_u32_e32 v158, s59, v220
	s_add_u32 s18, s18, 0x100000
	s_addc_u32 s19, s19, 0
	s_mov_b32 m0, s35
	v_lshl_add_u64 v[248:249], s[18:19], 0, v[178:179]
	global_load_lds_dwordx4 v[248:249], off
	v_lshl_add_u64 v[248:249], s[18:19], 0, v[180:181]
	s_mov_b32 m0, s86
	s_nop 0
	global_load_lds_dwordx4 v[248:249], off
	ds_read_b128 v[130:133], v142
	ds_read_b128 v[134:137], v142 offset:1024
	ds_read_b128 v[138:141], v142 offset:2048
	ds_read_b128 v[142:145], v142 offset:3072
	ds_read_b128 v[146:149], v158
	ds_read_b128 v[150:153], v158 offset:1024
	ds_read_b128 v[154:157], v158 offset:2048
	ds_read_b128 v[158:161], v158 offset:3072
	ds_read_b128 v[162:165], v233 offset:32768
	ds_read_b128 v[166:169], v233 offset:33792
	ds_read_b128 v[170:173], v233 offset:34816
	ds_read_b128 v[174:177], v233 offset:35840
	ds_read_b128 v[202:205], v233 offset:36864
	ds_read_b128 v[206:209], v233 offset:37888
	ds_read_b128 v[210:213], v233 offset:38912
	ds_read_b128 v[214:217], v233 offset:39936
	s_waitcnt vmcnt(8)
	s_waitcnt lgkmcnt(0)
	s_setprio 1
	s_barrier
	v_mfma_f32_16x16x32_bf16 v[90:93], v[130:133], v[162:165], v[90:93]
	v_mfma_f32_16x16x32_bf16 v[58:61], v[138:141], v[162:165], v[58:61]
	v_mfma_f32_16x16x32_bf16 v[98:101], v[130:133], v[170:173], v[98:101]
	v_mfma_f32_16x16x32_bf16 v[66:69], v[138:141], v[170:173], v[66:69]
	v_mfma_f32_16x16x32_bf16 v[102:105], v[130:133], v[202:205], v[102:105]
	v_mfma_f32_16x16x32_bf16 v[70:73], v[138:141], v[202:205], v[70:73]
	v_mfma_f32_16x16x32_bf16 v[110:113], v[130:133], v[210:213], v[110:113]
	v_mfma_f32_16x16x32_bf16 v[78:81], v[138:141], v[210:213], v[78:81]
	v_mfma_f32_16x16x32_bf16 v[90:93], v[134:137], v[166:169], v[90:93]
	v_mfma_f32_16x16x32_bf16 v[58:61], v[142:145], v[166:169], v[58:61]
	v_mfma_f32_16x16x32_bf16 v[98:101], v[134:137], v[174:177], v[98:101]
	v_mfma_f32_16x16x32_bf16 v[66:69], v[142:145], v[174:177], v[66:69]
	v_mfma_f32_16x16x32_bf16 v[102:105], v[134:137], v[206:209], v[102:105]
	v_mfma_f32_16x16x32_bf16 v[70:73], v[142:145], v[206:209], v[70:73]
	v_mfma_f32_16x16x32_bf16 v[110:113], v[134:137], v[214:217], v[110:113]
	v_mfma_f32_16x16x32_bf16 v[78:81], v[142:145], v[214:217], v[78:81]
	v_mfma_f32_16x16x32_bf16 v[26:29], v[146:149], v[162:165], v[26:29]
	v_mfma_f32_16x16x32_bf16 v[2:5], v[154:157], v[162:165], v[2:5]
	v_mfma_f32_16x16x32_bf16 v[34:37], v[146:149], v[170:173], v[34:37]
	v_mfma_f32_16x16x32_bf16 v[6:9], v[154:157], v[170:173], v[6:9]
	v_mfma_f32_16x16x32_bf16 v[38:41], v[146:149], v[202:205], v[38:41]
	v_mfma_f32_16x16x32_bf16 v[10:13], v[154:157], v[202:205], v[10:13]
	v_mfma_f32_16x16x32_bf16 v[46:49], v[146:149], v[210:213], v[46:49]
	v_mfma_f32_16x16x32_bf16 v[14:17], v[154:157], v[210:213], v[14:17]
	v_mfma_f32_16x16x32_bf16 v[26:29], v[150:153], v[166:169], v[26:29]
	v_mfma_f32_16x16x32_bf16 v[2:5], v[158:161], v[166:169], v[2:5]
	v_mfma_f32_16x16x32_bf16 v[34:37], v[150:153], v[174:177], v[34:37]
	v_mfma_f32_16x16x32_bf16 v[6:9], v[158:161], v[174:177], v[6:9]
	v_mfma_f32_16x16x32_bf16 v[38:41], v[150:153], v[206:209], v[38:41]
	v_mfma_f32_16x16x32_bf16 v[10:13], v[158:161], v[206:209], v[10:13]
	v_mfma_f32_16x16x32_bf16 v[46:49], v[150:153], v[214:217], v[46:49]
	v_mfma_f32_16x16x32_bf16 v[14:17], v[158:161], v[214:217], v[14:17]
	s_barrier
	s_setprio 0
	s_add_i32 s18, s27, s15
	v_lshl_add_u64 v[218:219], v[218:219], 0, s[44:45]
	s_mov_b32 m0, s18
	s_nop 0
	global_load_lds_dwordx4 v[218:219], off
	s_add_i32 m0, s18, 0x2000
	s_add_u32 s16, s16, 0x100080
	v_lshl_add_u64 v[218:219], v[242:243], 0, s[44:45]
	s_addc_u32 s17, s17, 0
	s_add_i32 s18, s59, s15
	global_load_lds_dwordx4 v[218:219], off
	v_lshl_add_u64 v[218:219], s[16:17], 0, v[178:179]
	s_mov_b32 m0, s18
	s_nop 0
	global_load_lds_dwordx4 v[218:219], off
	v_lshl_add_u64 v[218:219], s[16:17], 0, v[180:181]
	s_add_i32 m0, s18, 0x2000
	s_nop 0
	global_load_lds_dwordx4 v[218:219], off
	v_lshl_add_u64 v[218:219], v[244:245], 0, s[44:45]
	s_mov_b32 m0, s66
	s_nop 0
	global_load_lds_dwordx4 v[218:219], off
	v_lshl_add_u64 v[218:219], v[246:247], 0, s[44:45]
	s_mov_b32 m0, s67
	s_nop 0
	global_load_lds_dwordx4 v[218:219], off
	ds_read_b128 v[162:165], v233 offset:49152
	ds_read_b128 v[166:169], v233 offset:50176
	ds_read_b128 v[170:173], v233 offset:51200
	ds_read_b128 v[174:177], v233 offset:52224
	ds_read_b128 v[202:205], v233 offset:53248
	ds_read_b128 v[206:209], v233 offset:54272
	ds_read_b128 v[210:213], v233 offset:55296
	ds_read_b128 v[214:217], v233 offset:56320
	s_waitcnt vmcnt(8)
	s_waitcnt lgkmcnt(0)
	s_setprio 1
	s_barrier
	v_mfma_f32_16x16x32_bf16 v[114:117], v[130:133], v[162:165], v[114:117]
	v_mfma_f32_16x16x32_bf16 v[82:85], v[138:141], v[162:165], v[82:85]
	v_mfma_f32_16x16x32_bf16 v[118:121], v[130:133], v[170:173], v[118:121]
	v_mfma_f32_16x16x32_bf16 v[86:89], v[138:141], v[170:173], v[86:89]
	v_mfma_f32_16x16x32_bf16 v[122:125], v[130:133], v[202:205], v[122:125]
	v_mfma_f32_16x16x32_bf16 v[94:97], v[138:141], v[202:205], v[94:97]
	v_mfma_f32_16x16x32_bf16 v[126:129], v[130:133], v[210:213], v[126:129]
	v_mfma_f32_16x16x32_bf16 v[106:109], v[138:141], v[210:213], v[106:109]
	v_mfma_f32_16x16x32_bf16 v[114:117], v[134:137], v[166:169], v[114:117]
	v_mfma_f32_16x16x32_bf16 v[82:85], v[142:145], v[166:169], v[82:85]
	v_mfma_f32_16x16x32_bf16 v[118:121], v[134:137], v[174:177], v[118:121]
	v_mfma_f32_16x16x32_bf16 v[86:89], v[142:145], v[174:177], v[86:89]
	v_mfma_f32_16x16x32_bf16 v[122:125], v[134:137], v[206:209], v[122:125]
	v_mfma_f32_16x16x32_bf16 v[94:97], v[142:145], v[206:209], v[94:97]
	v_mfma_f32_16x16x32_bf16 v[126:129], v[134:137], v[214:217], v[126:129]
	v_mfma_f32_16x16x32_bf16 v[106:109], v[142:145], v[214:217], v[106:109]
	v_mfma_f32_16x16x32_bf16 v[50:53], v[146:149], v[162:165], v[50:53]
	v_mfma_f32_16x16x32_bf16 v[18:21], v[154:157], v[162:165], v[18:21]
	v_mfma_f32_16x16x32_bf16 v[54:57], v[146:149], v[170:173], v[54:57]
	v_mfma_f32_16x16x32_bf16 v[22:25], v[154:157], v[170:173], v[22:25]
	v_mfma_f32_16x16x32_bf16 v[62:65], v[146:149], v[202:205], v[62:65]
	v_mfma_f32_16x16x32_bf16 v[30:33], v[154:157], v[202:205], v[30:33]
	v_mfma_f32_16x16x32_bf16 v[74:77], v[146:149], v[210:213], v[74:77]
	v_mfma_f32_16x16x32_bf16 v[42:45], v[154:157], v[210:213], v[42:45]
	v_mfma_f32_16x16x32_bf16 v[50:53], v[150:153], v[166:169], v[50:53]
	v_mfma_f32_16x16x32_bf16 v[18:21], v[158:161], v[166:169], v[18:21]
	v_mfma_f32_16x16x32_bf16 v[54:57], v[150:153], v[174:177], v[54:57]
	v_mfma_f32_16x16x32_bf16 v[22:25], v[158:161], v[174:177], v[22:25]
	v_mfma_f32_16x16x32_bf16 v[62:65], v[150:153], v[206:209], v[62:65]
	v_mfma_f32_16x16x32_bf16 v[30:33], v[158:161], v[206:209], v[30:33]
	v_mfma_f32_16x16x32_bf16 v[74:77], v[150:153], v[214:217], v[74:77]
	v_mfma_f32_16x16x32_bf16 v[42:45], v[158:161], v[214:217], v[42:45]
	s_barrier
	s_setprio 0
	s_add_i32 s26, s26, 2
	s_add_u32 s0, s0, 0x100
	s_addc_u32 s1, s1, 0
	s_add_u32 s24, s24, 0x100
	s_addc_u32 s25, s25, 0
	s_cmp_gt_u32 s26, 61
	s_cbranch_scc0 .LBB0_672
	s_and_b64 vcc, exec, s[90:91]
	s_cbranch_vccz .LBB0_675
	s_barrier

.Lpeelc:
	s_add_u32 s36, s26, 0xfff00080
	s_addc_u32 s37, s27, -1
	s_cmp_eq_u32 s54, 60
	s_cselect_b32 s39, s19, s37
	s_cselect_b32 s38, s50, s36
	s_cselect_b32 s37, s17, s53
	s_cselect_b32 s36, s51, s52
	v_lshl_add_u64 v[148:149], s[26:27], 0, v[140:141]
	s_add_i32 m0, s25, 0xc000
	s_nop 0
	global_load_lds_dwordx4 v[148:149], off
	v_lshl_add_u64 v[148:149], s[26:27], 0, v[142:143]
	s_add_i32 m0, s25, 0xe000
	s_nop 0
	global_load_lds_dwordx4 v[148:149], off
	ds_read_b128 v[156:159], v153
	ds_read_b128 v[160:163], v153 offset:1024
	ds_read_b128 v[164:167], v153 offset:2048
	ds_read_b128 v[168:171], v153 offset:3072
	ds_read_b128 v[172:175], v154
	ds_read_b128 v[176:179], v154 offset:1024
	ds_read_b128 v[180:183], v154 offset:2048
	ds_read_b128 v[184:187], v154 offset:3072
	ds_read_b128 v[188:191], v155
	ds_read_b128 v[192:195], v155 offset:1024
	ds_read_b128 v[196:199], v155 offset:2048
	ds_read_b128 v[200:203], v155 offset:3072
	ds_read_b128 v[204:207], v155 offset:4096
	ds_read_b128 v[208:211], v155 offset:5120
	ds_read_b128 v[212:215], v155 offset:6144
	ds_read_b128 v[216:219], v155 offset:7168
	s_waitcnt vmcnt(8)
	s_waitcnt lgkmcnt(0)
	s_setprio 1
	s_barrier
	v_mfma_f32_16x16x32_bf16 v[126:129], v[156:159], v[188:191], 0
	v_mfma_f32_16x16x32_bf16 v[122:125], v[164:167], v[188:191], 0
	v_mfma_f32_16x16x32_bf16 v[118:121], v[156:159], v[196:199], 0
	v_mfma_f32_16x16x32_bf16 v[114:117], v[164:167], v[196:199], 0
	v_mfma_f32_16x16x32_bf16 v[94:97], v[156:159], v[204:207], 0
	v_mfma_f32_16x16x32_bf16 v[90:93], v[164:167], v[204:207], 0
	v_mfma_f32_16x16x32_bf16 v[86:89], v[156:159], v[212:215], 0
	v_mfma_f32_16x16x32_bf16 v[82:85], v[164:167], v[212:215], 0
	v_mfma_f32_16x16x32_bf16 v[126:129], v[160:163], v[192:195], v[126:129]
	v_mfma_f32_16x16x32_bf16 v[122:125], v[168:171], v[192:195], v[122:125]
	v_mfma_f32_16x16x32_bf16 v[118:121], v[160:163], v[200:203], v[118:121]
	v_mfma_f32_16x16x32_bf16 v[114:117], v[168:171], v[200:203], v[114:117]
	v_mfma_f32_16x16x32_bf16 v[94:97], v[160:163], v[208:211], v[94:97]
	v_mfma_f32_16x16x32_bf16 v[90:93], v[168:171], v[208:211], v[90:93]
	v_mfma_f32_16x16x32_bf16 v[86:89], v[160:163], v[216:219], v[86:89]
	v_mfma_f32_16x16x32_bf16 v[82:85], v[168:171], v[216:219], v[82:85]
	v_mfma_f32_16x16x32_bf16 v[110:113], v[172:175], v[188:191], 0
	v_mfma_f32_16x16x32_bf16 v[106:109], v[180:183], v[188:191], 0
	v_mfma_f32_16x16x32_bf16 v[102:105], v[172:175], v[196:199], 0
	v_mfma_f32_16x16x32_bf16 v[98:101], v[180:183], v[196:199], 0
	v_mfma_f32_16x16x32_bf16 v[78:81], v[172:175], v[204:207], 0
	v_mfma_f32_16x16x32_bf16 v[74:77], v[180:183], v[204:207], 0
	v_mfma_f32_16x16x32_bf16 v[70:73], v[172:175], v[212:215], 0
	v_mfma_f32_16x16x32_bf16 v[66:69], v[180:183], v[212:215], 0
	v_mfma_f32_16x16x32_bf16 v[110:113], v[176:179], v[192:195], v[110:113]
	v_mfma_f32_16x16x32_bf16 v[106:109], v[184:187], v[192:195], v[106:109]
	v_mfma_f32_16x16x32_bf16 v[102:105], v[176:179], v[200:203], v[102:105]
	v_mfma_f32_16x16x32_bf16 v[98:101], v[184:187], v[200:203], v[98:101]
	v_mfma_f32_16x16x32_bf16 v[78:81], v[176:179], v[208:211], v[78:81]
	v_mfma_f32_16x16x32_bf16 v[74:77], v[184:187], v[208:211], v[74:77]
	v_mfma_f32_16x16x32_bf16 v[70:73], v[176:179], v[216:219], v[70:73]
	v_mfma_f32_16x16x32_bf16 v[66:69], v[184:187], v[216:219], v[66:69]
	s_barrier
	s_setprio 0
	s_add_i32 s55, s44, s13
	v_lshl_add_u64 v[148:149], s[36:37], 0, v[134:135]
	s_mov_b32 m0, s55
	s_nop 0
	global_load_lds_dwordx4 v[148:149], off
	s_add_i32 m0, s55, 0x2000
	s_add_u32 s56, s36, 0x100000
	v_lshl_add_u64 v[220:221], s[36:37], 0, v[130:131]
	s_addc_u32 s57, s37, 0
	s_add_i32 s55, s45, s13
	global_load_lds_dwordx4 v[220:221], off
	v_lshl_add_u64 v[224:225], s[56:57], 0, v[134:135]
	s_mov_b32 m0, s55
	v_lshl_add_u64 v[226:227], s[38:39], 0, v[132:133]
	global_load_lds_dwordx4 v[224:225], off
	v_lshl_add_u64 v[224:225], s[56:57], 0, v[130:131]
	s_add_i32 m0, s55, 0x2000
	s_nop 0
	global_load_lds_dwordx4 v[224:225], off
	v_lshl_add_u64 v[224:225], s[38:39], 0, v[136:137]
	s_mov_b32 m0, s25
	s_nop 0
	global_load_lds_dwordx4 v[224:225], off
	s_mov_b32 m0, s31
	s_nop 0
	global_load_lds_dwordx4 v[226:227], off
	ds_read_b128 v[188:191], v155 offset:16384
	ds_read_b128 v[192:195], v155 offset:17408
	ds_read_b128 v[196:199], v155 offset:18432
	ds_read_b128 v[200:203], v155 offset:19456
	ds_read_b128 v[204:207], v155 offset:20480
	ds_read_b128 v[208:211], v155 offset:21504
	ds_read_b128 v[212:215], v155 offset:22528
	ds_read_b128 v[216:219], v155 offset:23552
	s_waitcnt vmcnt(8)
	s_waitcnt lgkmcnt(0)
	s_setprio 1
	s_barrier
	v_mfma_f32_16x16x32_bf16 v[62:65], v[156:159], v[188:191], 0
	v_mfma_f32_16x16x32_bf16 v[58:61], v[164:167], v[188:191], 0
	v_mfma_f32_16x16x32_bf16 v[54:57], v[156:159], v[196:199], 0
	v_mfma_f32_16x16x32_bf16 v[50:53], v[164:167], v[196:199], 0
	v_mfma_f32_16x16x32_bf16 v[30:33], v[156:159], v[204:207], 0
	v_mfma_f32_16x16x32_bf16 v[26:29], v[164:167], v[204:207], 0
	v_mfma_f32_16x16x32_bf16 v[22:25], v[156:159], v[212:215], 0
	v_mfma_f32_16x16x32_bf16 v[18:21], v[164:167], v[212:215], 0
	v_mfma_f32_16x16x32_bf16 v[62:65], v[160:163], v[192:195], v[62:65]
	v_mfma_f32_16x16x32_bf16 v[58:61], v[168:171], v[192:195], v[58:61]
	v_mfma_f32_16x16x32_bf16 v[54:57], v[160:163], v[200:203], v[54:57]
	v_mfma_f32_16x16x32_bf16 v[50:53], v[168:171], v[200:203], v[50:53]
	v_mfma_f32_16x16x32_bf16 v[30:33], v[160:163], v[208:211], v[30:33]
	v_mfma_f32_16x16x32_bf16 v[26:29], v[168:171], v[208:211], v[26:29]
	v_mfma_f32_16x16x32_bf16 v[22:25], v[160:163], v[216:219], v[22:25]
	v_mfma_f32_16x16x32_bf16 v[18:21], v[168:171], v[216:219], v[18:21]
	v_mfma_f32_16x16x32_bf16 v[46:49], v[172:175], v[188:191], 0
	v_mfma_f32_16x16x32_bf16 v[42:45], v[180:183], v[188:191], 0
	v_mfma_f32_16x16x32_bf16 v[38:41], v[172:175], v[196:199], 0
	v_mfma_f32_16x16x32_bf16 v[34:37], v[180:183], v[196:199], 0
	v_mfma_f32_16x16x32_bf16 v[14:17], v[172:175], v[204:207], 0
	v_mfma_f32_16x16x32_bf16 v[10:13], v[180:183], v[204:207], 0
	v_mfma_f32_16x16x32_bf16 v[6:9], v[172:175], v[212:215], 0
	v_mfma_f32_16x16x32_bf16 v[2:5], v[180:183], v[212:215], 0
	v_mfma_f32_16x16x32_bf16 v[46:49], v[176:179], v[192:195], v[46:49]
	v_mfma_f32_16x16x32_bf16 v[42:45], v[184:187], v[192:195], v[42:45]
	v_mfma_f32_16x16x32_bf16 v[38:41], v[176:179], v[200:203], v[38:41]
	v_mfma_f32_16x16x32_bf16 v[34:37], v[184:187], v[200:203], v[34:37]
	v_mfma_f32_16x16x32_bf16 v[14:17], v[176:179], v[208:211], v[14:17]
	v_mfma_f32_16x16x32_bf16 v[10:13], v[184:187], v[208:211], v[10:13]
	v_mfma_f32_16x16x32_bf16 v[6:9], v[176:179], v[216:219], v[6:9]
	v_mfma_f32_16x16x32_bf16 v[2:5], v[184:187], v[216:219], v[2:5]
	s_barrier
	s_setprio 0
	s_add_i32 s55, 0, 0x18000
	s_add_i32 s56, 0, 0x1c000
	v_add_u32_e32 v168, s55, v151
	v_add_u32_e32 v184, s56, v151
	s_add_u32 s38, s38, 0x100000
	s_addc_u32 s39, s39, 0
	s_mov_b32 m0, s34
	v_lshl_add_u64 v[228:229], s[38:39], 0, v[136:137]
	global_load_lds_dwordx4 v[228:229], off
	v_lshl_add_u64 v[228:229], s[38:39], 0, v[132:133]
	s_mov_b32 m0, s35
	s_nop 0
	global_load_lds_dwordx4 v[228:229], off
	ds_read_b128 v[156:159], v168
	ds_read_b128 v[160:163], v168 offset:1024
	ds_read_b128 v[164:167], v168 offset:2048
	ds_read_b128 v[168:171], v168 offset:3072
	ds_read_b128 v[172:175], v184
	ds_read_b128 v[176:179], v184 offset:1024
	ds_read_b128 v[180:183], v184 offset:2048
	ds_read_b128 v[184:187], v184 offset:3072
	ds_read_b128 v[188:191], v155 offset:32768
	ds_read_b128 v[192:195], v155 offset:33792
	ds_read_b128 v[196:199], v155 offset:34816
	ds_read_b128 v[200:203], v155 offset:35840
	ds_read_b128 v[204:207], v155 offset:36864
	ds_read_b128 v[208:211], v155 offset:37888
	ds_read_b128 v[212:215], v155 offset:38912
	ds_read_b128 v[216:219], v155 offset:39936
	s_waitcnt vmcnt(8)
	s_waitcnt lgkmcnt(0)
	s_setprio 1
	s_barrier
	v_mfma_f32_16x16x32_bf16 v[126:129], v[156:159], v[188:191], v[126:129]
	v_mfma_f32_16x16x32_bf16 v[122:125], v[164:167], v[188:191], v[122:125]
	v_mfma_f32_16x16x32_bf16 v[118:121], v[156:159], v[196:199], v[118:121]
	v_mfma_f32_16x16x32_bf16 v[114:117], v[164:167], v[196:199], v[114:117]
	v_mfma_f32_16x16x32_bf16 v[94:97], v[156:159], v[204:207], v[94:97]
	v_mfma_f32_16x16x32_bf16 v[90:93], v[164:167], v[204:207], v[90:93]
	v_mfma_f32_16x16x32_bf16 v[86:89], v[156:159], v[212:215], v[86:89]
	v_mfma_f32_16x16x32_bf16 v[82:85], v[164:167], v[212:215], v[82:85]
	v_mfma_f32_16x16x32_bf16 v[126:129], v[160:163], v[192:195], v[126:129]
	v_mfma_f32_16x16x32_bf16 v[122:125], v[168:171], v[192:195], v[122:125]
	v_mfma_f32_16x16x32_bf16 v[118:121], v[160:163], v[200:203], v[118:121]
	v_mfma_f32_16x16x32_bf16 v[114:117], v[168:171], v[200:203], v[114:117]
	v_mfma_f32_16x16x32_bf16 v[94:97], v[160:163], v[208:211], v[94:97]
	v_mfma_f32_16x16x32_bf16 v[90:93], v[168:171], v[208:211], v[90:93]
	v_mfma_f32_16x16x32_bf16 v[86:89], v[160:163], v[216:219], v[86:89]
	v_mfma_f32_16x16x32_bf16 v[82:85], v[168:171], v[216:219], v[82:85]
	v_mfma_f32_16x16x32_bf16 v[110:113], v[172:175], v[188:191], v[110:113]
	v_mfma_f32_16x16x32_bf16 v[106:109], v[180:183], v[188:191], v[106:109]
	v_mfma_f32_16x16x32_bf16 v[102:105], v[172:175], v[196:199], v[102:105]
	v_mfma_f32_16x16x32_bf16 v[98:101], v[180:183], v[196:199], v[98:101]
	v_mfma_f32_16x16x32_bf16 v[78:81], v[172:175], v[204:207], v[78:81]
	v_mfma_f32_16x16x32_bf16 v[74:77], v[180:183], v[204:207], v[74:77]
	v_mfma_f32_16x16x32_bf16 v[70:73], v[172:175], v[212:215], v[70:73]
	v_mfma_f32_16x16x32_bf16 v[66:69], v[180:183], v[212:215], v[66:69]
	v_mfma_f32_16x16x32_bf16 v[110:113], v[176:179], v[192:195], v[110:113]
	v_mfma_f32_16x16x32_bf16 v[106:109], v[184:187], v[192:195], v[106:109]
	v_mfma_f32_16x16x32_bf16 v[102:105], v[176:179], v[200:203], v[102:105]
	v_mfma_f32_16x16x32_bf16 v[98:101], v[184:187], v[200:203], v[98:101]
	v_mfma_f32_16x16x32_bf16 v[78:81], v[176:179], v[208:211], v[78:81]
	v_mfma_f32_16x16x32_bf16 v[74:77], v[184:187], v[208:211], v[74:77]
	v_mfma_f32_16x16x32_bf16 v[70:73], v[176:179], v[216:219], v[70:73]
	v_mfma_f32_16x16x32_bf16 v[66:69], v[184:187], v[216:219], v[66:69]
	s_barrier
	s_setprio 0
	s_add_i32 s38, s55, s13
	v_lshl_add_u64 v[148:149], v[148:149], 0, s[6:7]
	s_mov_b32 m0, s38
	s_nop 0
	global_load_lds_dwordx4 v[148:149], off
	s_add_i32 m0, s38, 0x2000
	s_add_u32 s36, s36, 0x100080
	v_lshl_add_u64 v[148:149], v[220:221], 0, s[6:7]
	s_addc_u32 s37, s37, 0
	s_add_i32 s38, s56, s13
	global_load_lds_dwordx4 v[148:149], off
	v_lshl_add_u64 v[148:149], s[36:37], 0, v[134:135]
	s_mov_b32 m0, s38
	s_nop 0
	global_load_lds_dwordx4 v[148:149], off
	v_lshl_add_u64 v[148:149], s[36:37], 0, v[130:131]
	s_add_i32 m0, s38, 0x2000
	s_nop 0
	global_load_lds_dwordx4 v[148:149], off
	v_lshl_add_u64 v[148:149], v[224:225], 0, s[6:7]
	s_mov_b32 m0, s41
	s_nop 0
	global_load_lds_dwordx4 v[148:149], off
	v_lshl_add_u64 v[148:149], v[226:227], 0, s[6:7]
	s_mov_b32 m0, s42
	s_nop 0
	global_load_lds_dwordx4 v[148:149], off
	ds_read_b128 v[188:191], v155 offset:49152
	ds_read_b128 v[192:195], v155 offset:50176
	ds_read_b128 v[196:199], v155 offset:51200
	ds_read_b128 v[200:203], v155 offset:52224
	ds_read_b128 v[204:207], v155 offset:53248
	ds_read_b128 v[208:211], v155 offset:54272
	ds_read_b128 v[212:215], v155 offset:55296
	ds_read_b128 v[216:219], v155 offset:56320
	s_waitcnt vmcnt(8)
	s_waitcnt lgkmcnt(0)
	s_setprio 1
	s_barrier
	v_mfma_f32_16x16x32_bf16 v[62:65], v[156:159], v[188:191], v[62:65]
	v_mfma_f32_16x16x32_bf16 v[58:61], v[164:167], v[188:191], v[58:61]
	v_mfma_f32_16x16x32_bf16 v[54:57], v[156:159], v[196:199], v[54:57]
	v_mfma_f32_16x16x32_bf16 v[50:53], v[164:167], v[196:199], v[50:53]
	v_mfma_f32_16x16x32_bf16 v[30:33], v[156:159], v[204:207], v[30:33]
	v_mfma_f32_16x16x32_bf16 v[26:29], v[164:167], v[204:207], v[26:29]
	v_mfma_f32_16x16x32_bf16 v[22:25], v[156:159], v[212:215], v[22:25]
	v_mfma_f32_16x16x32_bf16 v[18:21], v[164:167], v[212:215], v[18:21]
	v_mfma_f32_16x16x32_bf16 v[62:65], v[160:163], v[192:195], v[62:65]
	v_mfma_f32_16x16x32_bf16 v[58:61], v[168:171], v[192:195], v[58:61]
	v_mfma_f32_16x16x32_bf16 v[54:57], v[160:163], v[200:203], v[54:57]
	v_mfma_f32_16x16x32_bf16 v[50:53], v[168:171], v[200:203], v[50:53]
	v_mfma_f32_16x16x32_bf16 v[30:33], v[160:163], v[208:211], v[30:33]
	v_mfma_f32_16x16x32_bf16 v[26:29], v[168:171], v[208:211], v[26:29]
	v_mfma_f32_16x16x32_bf16 v[22:25], v[160:163], v[216:219], v[22:25]
	v_mfma_f32_16x16x32_bf16 v[18:21], v[168:171], v[216:219], v[18:21]
	v_mfma_f32_16x16x32_bf16 v[46:49], v[172:175], v[188:191], v[46:49]
	v_mfma_f32_16x16x32_bf16 v[42:45], v[180:183], v[188:191], v[42:45]
	v_mfma_f32_16x16x32_bf16 v[38:41], v[172:175], v[196:199], v[38:41]
	v_mfma_f32_16x16x32_bf16 v[34:37], v[180:183], v[196:199], v[34:37]
	v_mfma_f32_16x16x32_bf16 v[14:17], v[172:175], v[204:207], v[14:17]
	v_mfma_f32_16x16x32_bf16 v[10:13], v[180:183], v[204:207], v[10:13]
	v_mfma_f32_16x16x32_bf16 v[6:9], v[172:175], v[212:215], v[6:9]
	v_mfma_f32_16x16x32_bf16 v[2:5], v[180:183], v[212:215], v[2:5]
	v_mfma_f32_16x16x32_bf16 v[46:49], v[176:179], v[192:195], v[46:49]
	v_mfma_f32_16x16x32_bf16 v[42:45], v[184:187], v[192:195], v[42:45]
	v_mfma_f32_16x16x32_bf16 v[38:41], v[176:179], v[200:203], v[38:41]
	v_mfma_f32_16x16x32_bf16 v[34:37], v[184:187], v[200:203], v[34:37]
	v_mfma_f32_16x16x32_bf16 v[14:17], v[176:179], v[208:211], v[14:17]
	v_mfma_f32_16x16x32_bf16 v[10:13], v[184:187], v[208:211], v[10:13]
	v_mfma_f32_16x16x32_bf16 v[6:9], v[176:179], v[216:219], v[6:9]
	v_mfma_f32_16x16x32_bf16 v[2:5], v[184:187], v[216:219], v[2:5]
	s_barrier
	s_setprio 0
	s_add_i32 s54, s54, 2
	s_add_u32 s26, s26, 0x100
	s_addc_u32 s27, s27, 0
	s_add_u32 s52, s52, 0x100
	s_addc_u32 s53, s53, 0
.LBB0_788:
	s_add_u32 s36, s26, 0xfff00080
	s_addc_u32 s37, s27, -1
	s_cmp_eq_u32 s54, 60
	s_cselect_b32 s39, s19, s37
	s_cselect_b32 s38, s50, s36
	s_cselect_b32 s37, s17, s53
	s_cselect_b32 s36, s51, s52
	v_lshl_add_u64 v[148:149], s[26:27], 0, v[140:141]
	s_add_i32 m0, s25, 0xc000
	s_nop 0
	global_load_lds_dwordx4 v[148:149], off
	v_lshl_add_u64 v[148:149], s[26:27], 0, v[142:143]
	s_add_i32 m0, s25, 0xe000
	s_nop 0
	global_load_lds_dwordx4 v[148:149], off
	ds_read_b128 v[156:159], v153
	ds_read_b128 v[160:163], v153 offset:1024
	ds_read_b128 v[164:167], v153 offset:2048
	ds_read_b128 v[168:171], v153 offset:3072
	ds_read_b128 v[172:175], v154
	ds_read_b128 v[176:179], v154 offset:1024
	ds_read_b128 v[180:183], v154 offset:2048
	ds_read_b128 v[184:187], v154 offset:3072
	ds_read_b128 v[188:191], v155
	ds_read_b128 v[192:195], v155 offset:1024
	ds_read_b128 v[196:199], v155 offset:2048
	ds_read_b128 v[200:203], v155 offset:3072
	ds_read_b128 v[204:207], v155 offset:4096
	ds_read_b128 v[208:211], v155 offset:5120
	ds_read_b128 v[212:215], v155 offset:6144
	ds_read_b128 v[216:219], v155 offset:7168
	s_waitcnt vmcnt(8)
	s_waitcnt lgkmcnt(0)
	s_setprio 1
	s_barrier
	v_mfma_f32_16x16x32_bf16 v[126:129], v[156:159], v[188:191], v[126:129]
	v_mfma_f32_16x16x32_bf16 v[122:125], v[164:167], v[188:191], v[122:125]
	v_mfma_f32_16x16x32_bf16 v[118:121], v[156:159], v[196:199], v[118:121]
	v_mfma_f32_16x16x32_bf16 v[114:117], v[164:167], v[196:199], v[114:117]
	v_mfma_f32_16x16x32_bf16 v[94:97], v[156:159], v[204:207], v[94:97]
	v_mfma_f32_16x16x32_bf16 v[90:93], v[164:167], v[204:207], v[90:93]
	v_mfma_f32_16x16x32_bf16 v[86:89], v[156:159], v[212:215], v[86:89]
	v_mfma_f32_16x16x32_bf16 v[82:85], v[164:167], v[212:215], v[82:85]
	v_mfma_f32_16x16x32_bf16 v[126:129], v[160:163], v[192:195], v[126:129]
	v_mfma_f32_16x16x32_bf16 v[122:125], v[168:171], v[192:195], v[122:125]
	v_mfma_f32_16x16x32_bf16 v[118:121], v[160:163], v[200:203], v[118:121]
	v_mfma_f32_16x16x32_bf16 v[114:117], v[168:171], v[200:203], v[114:117]
	v_mfma_f32_16x16x32_bf16 v[94:97], v[160:163], v[208:211], v[94:97]
	v_mfma_f32_16x16x32_bf16 v[90:93], v[168:171], v[208:211], v[90:93]
	v_mfma_f32_16x16x32_bf16 v[86:89], v[160:163], v[216:219], v[86:89]
	v_mfma_f32_16x16x32_bf16 v[82:85], v[168:171], v[216:219], v[82:85]
	v_mfma_f32_16x16x32_bf16 v[110:113], v[172:175], v[188:191], v[110:113]
	v_mfma_f32_16x16x32_bf16 v[106:109], v[180:183], v[188:191], v[106:109]
	v_mfma_f32_16x16x32_bf16 v[102:105], v[172:175], v[196:199], v[102:105]
	v_mfma_f32_16x16x32_bf16 v[98:101], v[180:183], v[196:199], v[98:101]
	v_mfma_f32_16x16x32_bf16 v[78:81], v[172:175], v[204:207], v[78:81]
	v_mfma_f32_16x16x32_bf16 v[74:77], v[180:183], v[204:207], v[74:77]
	v_mfma_f32_16x16x32_bf16 v[70:73], v[172:175], v[212:215], v[70:73]
	v_mfma_f32_16x16x32_bf16 v[66:69], v[180:183], v[212:215], v[66:69]
	v_mfma_f32_16x16x32_bf16 v[110:113], v[176:179], v[192:195], v[110:113]
	v_mfma_f32_16x16x32_bf16 v[106:109], v[184:187], v[192:195], v[106:109]
	v_mfma_f32_16x16x32_bf16 v[102:105], v[176:179], v[200:203], v[102:105]
	v_mfma_f32_16x16x32_bf16 v[98:101], v[184:187], v[200:203], v[98:101]
	v_mfma_f32_16x16x32_bf16 v[78:81], v[176:179], v[208:211], v[78:81]
	v_mfma_f32_16x16x32_bf16 v[74:77], v[184:187], v[208:211], v[74:77]
	v_mfma_f32_16x16x32_bf16 v[70:73], v[176:179], v[216:219], v[70:73]
	v_mfma_f32_16x16x32_bf16 v[66:69], v[184:187], v[216:219], v[66:69]
	s_barrier
	s_setprio 0
	s_add_i32 s55, s44, s13
	v_lshl_add_u64 v[148:149], s[36:37], 0, v[134:135]
	s_mov_b32 m0, s55
	s_nop 0
	global_load_lds_dwordx4 v[148:149], off
	s_add_i32 m0, s55, 0x2000
	s_add_u32 s56, s36, 0x100000
	v_lshl_add_u64 v[220:221], s[36:37], 0, v[130:131]
	s_addc_u32 s57, s37, 0
	s_add_i32 s55, s45, s13
	global_load_lds_dwordx4 v[220:221], off
	v_lshl_add_u64 v[224:225], s[56:57], 0, v[134:135]
	s_mov_b32 m0, s55
	v_lshl_add_u64 v[226:227], s[38:39], 0, v[132:133]
	global_load_lds_dwordx4 v[224:225], off
	v_lshl_add_u64 v[224:225], s[56:57], 0, v[130:131]
	s_add_i32 m0, s55, 0x2000
	s_nop 0
	global_load_lds_dwordx4 v[224:225], off
	v_lshl_add_u64 v[224:225], s[38:39], 0, v[136:137]
	s_mov_b32 m0, s25
	s_nop 0
	global_load_lds_dwordx4 v[224:225], off
	s_mov_b32 m0, s31
	s_nop 0
	global_load_lds_dwordx4 v[226:227], off
	ds_read_b128 v[188:191], v155 offset:16384
	ds_read_b128 v[192:195], v155 offset:17408
	ds_read_b128 v[196:199], v155 offset:18432
	ds_read_b128 v[200:203], v155 offset:19456
	ds_read_b128 v[204:207], v155 offset:20480
	ds_read_b128 v[208:211], v155 offset:21504
	ds_read_b128 v[212:215], v155 offset:22528
	ds_read_b128 v[216:219], v155 offset:23552
	s_waitcnt vmcnt(8)
	s_waitcnt lgkmcnt(0)
	s_setprio 1
	s_barrier
	v_mfma_f32_16x16x32_bf16 v[62:65], v[156:159], v[188:191], v[62:65]
	v_mfma_f32_16x16x32_bf16 v[58:61], v[164:167], v[188:191], v[58:61]
	v_mfma_f32_16x16x32_bf16 v[54:57], v[156:159], v[196:199], v[54:57]
	v_mfma_f32_16x16x32_bf16 v[50:53], v[164:167], v[196:199], v[50:53]
	v_mfma_f32_16x16x32_bf16 v[30:33], v[156:159], v[204:207], v[30:33]
	v_mfma_f32_16x16x32_bf16 v[26:29], v[164:167], v[204:207], v[26:29]
	v_mfma_f32_16x16x32_bf16 v[22:25], v[156:159], v[212:215], v[22:25]
	v_mfma_f32_16x16x32_bf16 v[18:21], v[164:167], v[212:215], v[18:21]
	v_mfma_f32_16x16x32_bf16 v[62:65], v[160:163], v[192:195], v[62:65]
	v_mfma_f32_16x16x32_bf16 v[58:61], v[168:171], v[192:195], v[58:61]
	v_mfma_f32_16x16x32_bf16 v[54:57], v[160:163], v[200:203], v[54:57]
	v_mfma_f32_16x16x32_bf16 v[50:53], v[168:171], v[200:203], v[50:53]
	v_mfma_f32_16x16x32_bf16 v[30:33], v[160:163], v[208:211], v[30:33]
	v_mfma_f32_16x16x32_bf16 v[26:29], v[168:171], v[208:211], v[26:29]
	v_mfma_f32_16x16x32_bf16 v[22:25], v[160:163], v[216:219], v[22:25]
	v_mfma_f32_16x16x32_bf16 v[18:21], v[168:171], v[216:219], v[18:21]
	v_mfma_f32_16x16x32_bf16 v[46:49], v[172:175], v[188:191], v[46:49]
	v_mfma_f32_16x16x32_bf16 v[42:45], v[180:183], v[188:191], v[42:45]
	v_mfma_f32_16x16x32_bf16 v[38:41], v[172:175], v[196:199], v[38:41]
	v_mfma_f32_16x16x32_bf16 v[34:37], v[180:183], v[196:199], v[34:37]
	v_mfma_f32_16x16x32_bf16 v[14:17], v[172:175], v[204:207], v[14:17]
	v_mfma_f32_16x16x32_bf16 v[10:13], v[180:183], v[204:207], v[10:13]
	v_mfma_f32_16x16x32_bf16 v[6:9], v[172:175], v[212:215], v[6:9]
	v_mfma_f32_16x16x32_bf16 v[2:5], v[180:183], v[212:215], v[2:5]
	v_mfma_f32_16x16x32_bf16 v[46:49], v[176:179], v[192:195], v[46:49]
	v_mfma_f32_16x16x32_bf16 v[42:45], v[184:187], v[192:195], v[42:45]
	v_mfma_f32_16x16x32_bf16 v[38:41], v[176:179], v[200:203], v[38:41]
	v_mfma_f32_16x16x32_bf16 v[34:37], v[184:187], v[200:203], v[34:37]
	v_mfma_f32_16x16x32_bf16 v[14:17], v[176:179], v[208:211], v[14:17]
	v_mfma_f32_16x16x32_bf16 v[10:13], v[184:187], v[208:211], v[10:13]
	v_mfma_f32_16x16x32_bf16 v[6:9], v[176:179], v[216:219], v[6:9]
	v_mfma_f32_16x16x32_bf16 v[2:5], v[184:187], v[216:219], v[2:5]
	s_barrier
	s_setprio 0
	s_add_i32 s55, 0, 0x18000
	s_add_i32 s56, 0, 0x1c000
	v_add_u32_e32 v168, s55, v151
	v_add_u32_e32 v184, s56, v151
	s_add_u32 s38, s38, 0x100000
	s_addc_u32 s39, s39, 0
	s_mov_b32 m0, s34
	v_lshl_add_u64 v[228:229], s[38:39], 0, v[136:137]
	global_load_lds_dwordx4 v[228:229], off
	v_lshl_add_u64 v[228:229], s[38:39], 0, v[132:133]
	s_mov_b32 m0, s35
	s_nop 0
	global_load_lds_dwordx4 v[228:229], off
	ds_read_b128 v[156:159], v168
	ds_read_b128 v[160:163], v168 offset:1024
	ds_read_b128 v[164:167], v168 offset:2048
	ds_read_b128 v[168:171], v168 offset:3072
	ds_read_b128 v[172:175], v184
	ds_read_b128 v[176:179], v184 offset:1024
	ds_read_b128 v[180:183], v184 offset:2048
	ds_read_b128 v[184:187], v184 offset:3072
	ds_read_b128 v[188:191], v155 offset:32768
	ds_read_b128 v[192:195], v155 offset:33792
	ds_read_b128 v[196:199], v155 offset:34816
	ds_read_b128 v[200:203], v155 offset:35840
	ds_read_b128 v[204:207], v155 offset:36864
	ds_read_b128 v[208:211], v155 offset:37888
	ds_read_b128 v[212:215], v155 offset:38912
	ds_read_b128 v[216:219], v155 offset:39936
	s_waitcnt vmcnt(8)
	s_waitcnt lgkmcnt(0)
	s_setprio 1
	s_barrier
	v_mfma_f32_16x16x32_bf16 v[126:129], v[156:159], v[188:191], v[126:129]
	v_mfma_f32_16x16x32_bf16 v[122:125], v[164:167], v[188:191], v[122:125]
	v_mfma_f32_16x16x32_bf16 v[118:121], v[156:159], v[196:199], v[118:121]
	v_mfma_f32_16x16x32_bf16 v[114:117], v[164:167], v[196:199], v[114:117]
	v_mfma_f32_16x16x32_bf16 v[94:97], v[156:159], v[204:207], v[94:97]
	v_mfma_f32_16x16x32_bf16 v[90:93], v[164:167], v[204:207], v[90:93]
	v_mfma_f32_16x16x32_bf16 v[86:89], v[156:159], v[212:215], v[86:89]
	v_mfma_f32_16x16x32_bf16 v[82:85], v[164:167], v[212:215], v[82:85]
	v_mfma_f32_16x16x32_bf16 v[126:129], v[160:163], v[192:195], v[126:129]
	v_mfma_f32_16x16x32_bf16 v[122:125], v[168:171], v[192:195], v[122:125]
	v_mfma_f32_16x16x32_bf16 v[118:121], v[160:163], v[200:203], v[118:121]
	v_mfma_f32_16x16x32_bf16 v[114:117], v[168:171], v[200:203], v[114:117]
	v_mfma_f32_16x16x32_bf16 v[94:97], v[160:163], v[208:211], v[94:97]
	v_mfma_f32_16x16x32_bf16 v[90:93], v[168:171], v[208:211], v[90:93]
	v_mfma_f32_16x16x32_bf16 v[86:89], v[160:163], v[216:219], v[86:89]
	v_mfma_f32_16x16x32_bf16 v[82:85], v[168:171], v[216:219], v[82:85]
	v_mfma_f32_16x16x32_bf16 v[110:113], v[172:175], v[188:191], v[110:113]
	v_mfma_f32_16x16x32_bf16 v[106:109], v[180:183], v[188:191], v[106:109]
	v_mfma_f32_16x16x32_bf16 v[102:105], v[172:175], v[196:199], v[102:105]
	v_mfma_f32_16x16x32_bf16 v[98:101], v[180:183], v[196:199], v[98:101]
	v_mfma_f32_16x16x32_bf16 v[78:81], v[172:175], v[204:207], v[78:81]
	v_mfma_f32_16x16x32_bf16 v[74:77], v[180:183], v[204:207], v[74:77]
	v_mfma_f32_16x16x32_bf16 v[70:73], v[172:175], v[212:215], v[70:73]
	v_mfma_f32_16x16x32_bf16 v[66:69], v[180:183], v[212:215], v[66:69]
	v_mfma_f32_16x16x32_bf16 v[110:113], v[176:179], v[192:195], v[110:113]
	v_mfma_f32_16x16x32_bf16 v[106:109], v[184:187], v[192:195], v[106:109]
	v_mfma_f32_16x16x32_bf16 v[102:105], v[176:179], v[200:203], v[102:105]
	v_mfma_f32_16x16x32_bf16 v[98:101], v[184:187], v[200:203], v[98:101]
	v_mfma_f32_16x16x32_bf16 v[78:81], v[176:179], v[208:211], v[78:81]
	v_mfma_f32_16x16x32_bf16 v[74:77], v[184:187], v[208:211], v[74:77]
	v_mfma_f32_16x16x32_bf16 v[70:73], v[176:179], v[216:219], v[70:73]
	v_mfma_f32_16x16x32_bf16 v[66:69], v[184:187], v[216:219], v[66:69]
	s_barrier
	s_setprio 0
	s_add_i32 s38, s55, s13
	v_lshl_add_u64 v[148:149], v[148:149], 0, s[6:7]
	s_mov_b32 m0, s38
	s_nop 0
	global_load_lds_dwordx4 v[148:149], off
	s_add_i32 m0, s38, 0x2000
	s_add_u32 s36, s36, 0x100080
	v_lshl_add_u64 v[148:149], v[220:221], 0, s[6:7]
	s_addc_u32 s37, s37, 0
	s_add_i32 s38, s56, s13
	global_load_lds_dwordx4 v[148:149], off
	v_lshl_add_u64 v[148:149], s[36:37], 0, v[134:135]
	s_mov_b32 m0, s38
	s_nop 0
	global_load_lds_dwordx4 v[148:149], off
	v_lshl_add_u64 v[148:149], s[36:37], 0, v[130:131]
	s_add_i32 m0, s38, 0x2000
	s_nop 0
	global_load_lds_dwordx4 v[148:149], off
	v_lshl_add_u64 v[148:149], v[224:225], 0, s[6:7]
	s_mov_b32 m0, s41
	s_nop 0
	global_load_lds_dwordx4 v[148:149], off
	v_lshl_add_u64 v[148:149], v[226:227], 0, s[6:7]
	s_mov_b32 m0, s42
	s_nop 0
	global_load_lds_dwordx4 v[148:149], off
	ds_read_b128 v[188:191], v155 offset:49152
	ds_read_b128 v[192:195], v155 offset:50176
	ds_read_b128 v[196:199], v155 offset:51200
	ds_read_b128 v[200:203], v155 offset:52224
	ds_read_b128 v[204:207], v155 offset:53248
	ds_read_b128 v[208:211], v155 offset:54272
	ds_read_b128 v[212:215], v155 offset:55296
	ds_read_b128 v[216:219], v155 offset:56320
	s_waitcnt vmcnt(8)
	s_waitcnt lgkmcnt(0)
	s_setprio 1
	s_barrier
	v_mfma_f32_16x16x32_bf16 v[62:65], v[156:159], v[188:191], v[62:65]
	v_mfma_f32_16x16x32_bf16 v[58:61], v[164:167], v[188:191], v[58:61]
	v_mfma_f32_16x16x32_bf16 v[54:57], v[156:159], v[196:199], v[54:57]
	v_mfma_f32_16x16x32_bf16 v[50:53], v[164:167], v[196:199], v[50:53]
	v_mfma_f32_16x16x32_bf16 v[30:33], v[156:159], v[204:207], v[30:33]
	v_mfma_f32_16x16x32_bf16 v[26:29], v[164:167], v[204:207], v[26:29]
	v_mfma_f32_16x16x32_bf16 v[22:25], v[156:159], v[212:215], v[22:25]
	v_mfma_f32_16x16x32_bf16 v[18:21], v[164:167], v[212:215], v[18:21]
	v_mfma_f32_16x16x32_bf16 v[62:65], v[160:163], v[192:195], v[62:65]
	v_mfma_f32_16x16x32_bf16 v[58:61], v[168:171], v[192:195], v[58:61]
	v_mfma_f32_16x16x32_bf16 v[54:57], v[160:163], v[200:203], v[54:57]
	v_mfma_f32_16x16x32_bf16 v[50:53], v[168:171], v[200:203], v[50:53]
	v_mfma_f32_16x16x32_bf16 v[30:33], v[160:163], v[208:211], v[30:33]
	v_mfma_f32_16x16x32_bf16 v[26:29], v[168:171], v[208:211], v[26:29]
	v_mfma_f32_16x16x32_bf16 v[22:25], v[160:163], v[216:219], v[22:25]
	v_mfma_f32_16x16x32_bf16 v[18:21], v[168:171], v[216:219], v[18:21]
	v_mfma_f32_16x16x32_bf16 v[46:49], v[172:175], v[188:191], v[46:49]
	v_mfma_f32_16x16x32_bf16 v[42:45], v[180:183], v[188:191], v[42:45]
	v_mfma_f32_16x16x32_bf16 v[38:41], v[172:175], v[196:199], v[38:41]
	v_mfma_f32_16x16x32_bf16 v[34:37], v[180:183], v[196:199], v[34:37]
	v_mfma_f32_16x16x32_bf16 v[14:17], v[172:175], v[204:207], v[14:17]
	v_mfma_f32_16x16x32_bf16 v[10:13], v[180:183], v[204:207], v[10:13]
	v_mfma_f32_16x16x32_bf16 v[6:9], v[172:175], v[212:215], v[6:9]
	v_mfma_f32_16x16x32_bf16 v[2:5], v[180:183], v[212:215], v[2:5]
	v_mfma_f32_16x16x32_bf16 v[46:49], v[176:179], v[192:195], v[46:49]
	v_mfma_f32_16x16x32_bf16 v[42:45], v[184:187], v[192:195], v[42:45]
	v_mfma_f32_16x16x32_bf16 v[38:41], v[176:179], v[200:203], v[38:41]
	v_mfma_f32_16x16x32_bf16 v[34:37], v[184:187], v[200:203], v[34:37]
	v_mfma_f32_16x16x32_bf16 v[14:17], v[176:179], v[208:211], v[14:17]
	v_mfma_f32_16x16x32_bf16 v[10:13], v[184:187], v[208:211], v[10:13]
	v_mfma_f32_16x16x32_bf16 v[6:9], v[176:179], v[216:219], v[6:9]
	v_mfma_f32_16x16x32_bf16 v[2:5], v[184:187], v[216:219], v[2:5]
	s_barrier
	s_setprio 0
	s_add_i32 s54, s54, 2
	s_add_u32 s26, s26, 0x100
	s_addc_u32 s27, s27, 0
	s_add_u32 s52, s52, 0x100
	s_addc_u32 s53, s53, 0
	s_cmp_gt_u32 s54, 61
	s_cbranch_scc0 .LBB0_788
	s_and_b64 vcc, exec, s[8:9]
	s_cbranch_vccz .LBB0_791
	s_barrier

.Lpeeld:
	s_add_u32 s10, s8, 0xffd50080
	s_addc_u32 s11, s9, -1
	s_cmpk_eq_i32 s16, 0xa8
	s_cselect_b32 s13, s25, s11
	s_cselect_b32 s12, s24, s10
	s_cselect_b32 s11, s41, s15
	s_cselect_b32 s10, s40, s14
	v_lshl_add_u64 v[180:181], s[8:9], 0, v[166:167]
	s_add_i32 m0, s48, 0xc000
	s_nop 0
	global_load_lds_dwordx4 v[180:181], off
	v_lshl_add_u64 v[180:181], s[8:9], 0, v[168:169]
	s_add_i32 m0, s48, 0xe000
	s_nop 0
	global_load_lds_dwordx4 v[180:181], off
	ds_read_b128 v[130:133], v207
	ds_read_b128 v[134:137], v207 offset:1024
	ds_read_b128 v[138:141], v207 offset:2048
	ds_read_b128 v[142:145], v207 offset:3072
	ds_read_b128 v[146:149], v208
	ds_read_b128 v[172:175], v208 offset:1024
	ds_read_b128 v[176:179], v208 offset:2048
	ds_read_b128 v[210:213], v208 offset:3072
	ds_read_b128 v[214:217], v202
	ds_read_b128 v[218:221], v202 offset:1024
	ds_read_b128 v[224:227], v202 offset:2048
	ds_read_b128 v[228:231], v202 offset:3072
	ds_read_b128 v[232:235], v202 offset:4096
	ds_read_b128 v[236:239], v202 offset:5120
	ds_read_b128 v[240:243], v202 offset:6144
	ds_read_b128 v[244:247], v202 offset:7168
	s_waitcnt vmcnt(8)
	s_waitcnt lgkmcnt(0)
	s_setprio 1
	s_barrier
	v_mfma_f32_16x16x32_bf16 v[90:93], v[130:133], v[214:217], 0
	v_mfma_f32_16x16x32_bf16 v[74:77], v[138:141], v[214:217], 0
	v_mfma_f32_16x16x32_bf16 v[46:49], v[130:133], v[224:227], 0
	v_mfma_f32_16x16x32_bf16 v[42:45], v[138:141], v[224:227], 0
	v_mfma_f32_16x16x32_bf16 v[126:129], v[130:133], v[232:235], 0
	v_mfma_f32_16x16x32_bf16 v[122:125], v[138:141], v[232:235], 0
	v_mfma_f32_16x16x32_bf16 v[110:113], v[130:133], v[240:243], 0
	v_mfma_f32_16x16x32_bf16 v[106:109], v[138:141], v[240:243], 0
	v_mfma_f32_16x16x32_bf16 v[90:93], v[134:137], v[218:221], v[90:93]
	v_mfma_f32_16x16x32_bf16 v[74:77], v[142:145], v[218:221], v[74:77]
	v_mfma_f32_16x16x32_bf16 v[46:49], v[134:137], v[228:231], v[46:49]
	v_mfma_f32_16x16x32_bf16 v[42:45], v[142:145], v[228:231], v[42:45]
	v_mfma_f32_16x16x32_bf16 v[126:129], v[134:137], v[236:239], v[126:129]
	v_mfma_f32_16x16x32_bf16 v[122:125], v[142:145], v[236:239], v[122:125]
	v_mfma_f32_16x16x32_bf16 v[110:113], v[134:137], v[244:247], v[110:113]
	v_mfma_f32_16x16x32_bf16 v[106:109], v[142:145], v[244:247], v[106:109]
	v_mfma_f32_16x16x32_bf16 v[70:73], v[146:149], v[214:217], 0
	v_mfma_f32_16x16x32_bf16 v[66:69], v[176:179], v[214:217], 0
	v_mfma_f32_16x16x32_bf16 v[34:37], v[146:149], v[224:227], 0
	v_mfma_f32_16x16x32_bf16 v[38:41], v[176:179], v[224:227], 0
	v_mfma_f32_16x16x32_bf16 v[118:121], v[146:149], v[232:235], 0
	v_mfma_f32_16x16x32_bf16 v[114:117], v[176:179], v[232:235], 0
	v_mfma_f32_16x16x32_bf16 v[102:105], v[146:149], v[240:243], 0
	v_mfma_f32_16x16x32_bf16 v[98:101], v[176:179], v[240:243], 0
	v_mfma_f32_16x16x32_bf16 v[70:73], v[172:175], v[218:221], v[70:73]
	v_mfma_f32_16x16x32_bf16 v[66:69], v[210:213], v[218:221], v[66:69]
	v_mfma_f32_16x16x32_bf16 v[34:37], v[172:175], v[228:231], v[34:37]
	v_mfma_f32_16x16x32_bf16 v[38:41], v[210:213], v[228:231], v[38:41]
	v_mfma_f32_16x16x32_bf16 v[118:121], v[172:175], v[236:239], v[118:121]
	v_mfma_f32_16x16x32_bf16 v[114:117], v[210:213], v[236:239], v[114:117]
	v_mfma_f32_16x16x32_bf16 v[102:105], v[172:175], v[244:247], v[102:105]
	v_mfma_f32_16x16x32_bf16 v[98:101], v[210:213], v[244:247], v[98:101]
	s_barrier
	s_setprio 0
	s_add_i32 s17, s57, s46
	v_lshl_add_u64 v[180:181], s[10:11], 0, v[150:151]
	s_mov_b32 m0, s17
	s_nop 0
	global_load_lds_dwordx4 v[180:181], off
	s_add_i32 m0, s17, 0x2000
	s_add_u32 s18, s10, 0x2b0000
	v_lshl_add_u64 v[248:249], s[10:11], 0, v[152:153]
	s_addc_u32 s19, s11, 0
	s_add_i32 s17, s58, s46
	global_load_lds_dwordx4 v[248:249], off
	v_lshl_add_u64 v[250:251], s[18:19], 0, v[150:151]
	s_mov_b32 m0, s17
	v_lshl_add_u64 v[252:253], s[12:13], 0, v[152:153]
	global_load_lds_dwordx4 v[250:251], off
	v_lshl_add_u64 v[250:251], s[18:19], 0, v[152:153]
	s_add_i32 m0, s17, 0x2000
	s_nop 0
	global_load_lds_dwordx4 v[250:251], off
	v_lshl_add_u64 v[250:251], s[12:13], 0, v[150:151]
	s_mov_b32 m0, s48
	s_nop 0
	global_load_lds_dwordx4 v[250:251], off
	s_mov_b32 m0, s49
	s_nop 0
	global_load_lds_dwordx4 v[252:253], off
	ds_read_b128 v[214:217], v202 offset:16384
	ds_read_b128 v[218:221], v202 offset:17408
	ds_read_b128 v[224:227], v202 offset:18432
	ds_read_b128 v[228:231], v202 offset:19456
	ds_read_b128 v[232:235], v202 offset:20480
	ds_read_b128 v[236:239], v202 offset:21504
	ds_read_b128 v[240:243], v202 offset:22528
	ds_read_b128 v[244:247], v202 offset:23552
	s_waitcnt vmcnt(8)
	s_waitcnt lgkmcnt(0)
	s_setprio 1
	s_barrier
	v_mfma_f32_16x16x32_bf16 v[94:97], v[130:133], v[214:217], 0
	v_mfma_f32_16x16x32_bf16 v[86:89], v[138:141], v[214:217], 0
	v_mfma_f32_16x16x32_bf16 v[82:85], v[130:133], v[224:227], 0
	v_mfma_f32_16x16x32_bf16 v[78:81], v[138:141], v[224:227], 0
	v_mfma_f32_16x16x32_bf16 v[30:33], v[130:133], v[232:235], 0
	v_mfma_f32_16x16x32_bf16 v[26:29], v[138:141], v[232:235], 0
	v_mfma_f32_16x16x32_bf16 v[22:25], v[130:133], v[240:243], 0
	v_mfma_f32_16x16x32_bf16 v[18:21], v[138:141], v[240:243], 0
	v_mfma_f32_16x16x32_bf16 v[94:97], v[134:137], v[218:221], v[94:97]
	v_mfma_f32_16x16x32_bf16 v[86:89], v[142:145], v[218:221], v[86:89]
	v_mfma_f32_16x16x32_bf16 v[82:85], v[134:137], v[228:231], v[82:85]
	v_mfma_f32_16x16x32_bf16 v[78:81], v[142:145], v[228:231], v[78:81]
	v_mfma_f32_16x16x32_bf16 v[30:33], v[134:137], v[236:239], v[30:33]
	v_mfma_f32_16x16x32_bf16 v[26:29], v[142:145], v[236:239], v[26:29]
	v_mfma_f32_16x16x32_bf16 v[22:25], v[134:137], v[244:247], v[22:25]
	v_mfma_f32_16x16x32_bf16 v[18:21], v[142:145], v[244:247], v[18:21]
	v_mfma_f32_16x16x32_bf16 v[62:65], v[146:149], v[214:217], 0
	v_mfma_f32_16x16x32_bf16 v[58:61], v[176:179], v[214:217], 0
	v_mfma_f32_16x16x32_bf16 v[54:57], v[146:149], v[224:227], 0
	v_mfma_f32_16x16x32_bf16 v[50:53], v[176:179], v[224:227], 0
	v_mfma_f32_16x16x32_bf16 v[14:17], v[146:149], v[232:235], 0
	v_mfma_f32_16x16x32_bf16 v[6:9], v[176:179], v[232:235], 0
	v_mfma_f32_16x16x32_bf16 v[10:13], v[146:149], v[240:243], 0
	v_mfma_f32_16x16x32_bf16 v[2:5], v[176:179], v[240:243], 0
	v_mfma_f32_16x16x32_bf16 v[62:65], v[172:175], v[218:221], v[62:65]
	v_mfma_f32_16x16x32_bf16 v[58:61], v[210:213], v[218:221], v[58:61]
	v_mfma_f32_16x16x32_bf16 v[54:57], v[172:175], v[228:231], v[54:57]
	v_mfma_f32_16x16x32_bf16 v[50:53], v[210:213], v[228:231], v[50:53]
	v_mfma_f32_16x16x32_bf16 v[14:17], v[172:175], v[236:239], v[14:17]
	v_mfma_f32_16x16x32_bf16 v[6:9], v[210:213], v[236:239], v[6:9]
	v_mfma_f32_16x16x32_bf16 v[10:13], v[172:175], v[244:247], v[10:13]
	v_mfma_f32_16x16x32_bf16 v[2:5], v[210:213], v[244:247], v[2:5]
	s_barrier
	s_setprio 0
	s_add_i32 s17, 0, 0x18000
	s_add_i32 s18, 0, 0x1c000
	v_add_u32_e32 v142, s17, v182
	v_add_u32_e32 v154, s18, v182
	s_add_u32 s12, s12, 0x2b0000
	s_addc_u32 s13, s13, 0
	s_mov_b32 m0, s50
	v_lshl_add_u64 v[188:189], s[12:13], 0, v[150:151]
	global_load_lds_dwordx4 v[188:189], off
	v_lshl_add_u64 v[188:189], s[12:13], 0, v[152:153]
	s_mov_b32 m0, s51
	s_nop 0
	global_load_lds_dwordx4 v[188:189], off
	ds_read_b128 v[130:133], v142
	ds_read_b128 v[134:137], v142 offset:1024
	ds_read_b128 v[138:141], v142 offset:2048
	ds_read_b128 v[142:145], v142 offset:3072
	ds_read_b128 v[146:149], v154
	ds_read_b128 v[172:175], v154 offset:1024
	ds_read_b128 v[176:179], v154 offset:2048
	ds_read_b128 v[210:213], v154 offset:3072
	ds_read_b128 v[214:217], v202 offset:32768
	ds_read_b128 v[218:221], v202 offset:33792
	ds_read_b128 v[224:227], v202 offset:34816
	ds_read_b128 v[228:231], v202 offset:35840
	ds_read_b128 v[232:235], v202 offset:36864
	ds_read_b128 v[236:239], v202 offset:37888
	ds_read_b128 v[240:243], v202 offset:38912
	ds_read_b128 v[244:247], v202 offset:39936
	s_waitcnt vmcnt(8)
	s_waitcnt lgkmcnt(0)
	s_setprio 1
	s_barrier
	v_mfma_f32_16x16x32_bf16 v[90:93], v[130:133], v[214:217], v[90:93]
	v_mfma_f32_16x16x32_bf16 v[74:77], v[138:141], v[214:217], v[74:77]
	v_mfma_f32_16x16x32_bf16 v[46:49], v[130:133], v[224:227], v[46:49]
	v_mfma_f32_16x16x32_bf16 v[42:45], v[138:141], v[224:227], v[42:45]
	v_mfma_f32_16x16x32_bf16 v[126:129], v[130:133], v[232:235], v[126:129]
	v_mfma_f32_16x16x32_bf16 v[122:125], v[138:141], v[232:235], v[122:125]
	v_mfma_f32_16x16x32_bf16 v[110:113], v[130:133], v[240:243], v[110:113]
	v_mfma_f32_16x16x32_bf16 v[106:109], v[138:141], v[240:243], v[106:109]
	v_mfma_f32_16x16x32_bf16 v[90:93], v[134:137], v[218:221], v[90:93]
	v_mfma_f32_16x16x32_bf16 v[74:77], v[142:145], v[218:221], v[74:77]
	v_mfma_f32_16x16x32_bf16 v[46:49], v[134:137], v[228:231], v[46:49]
	v_mfma_f32_16x16x32_bf16 v[42:45], v[142:145], v[228:231], v[42:45]
	v_mfma_f32_16x16x32_bf16 v[126:129], v[134:137], v[236:239], v[126:129]
	v_mfma_f32_16x16x32_bf16 v[122:125], v[142:145], v[236:239], v[122:125]
	v_mfma_f32_16x16x32_bf16 v[110:113], v[134:137], v[244:247], v[110:113]
	v_mfma_f32_16x16x32_bf16 v[106:109], v[142:145], v[244:247], v[106:109]
	v_mfma_f32_16x16x32_bf16 v[70:73], v[146:149], v[214:217], v[70:73]
	v_mfma_f32_16x16x32_bf16 v[66:69], v[176:179], v[214:217], v[66:69]
	v_mfma_f32_16x16x32_bf16 v[34:37], v[146:149], v[224:227], v[34:37]
	v_mfma_f32_16x16x32_bf16 v[38:41], v[176:179], v[224:227], v[38:41]
	v_mfma_f32_16x16x32_bf16 v[118:121], v[146:149], v[232:235], v[118:121]
	v_mfma_f32_16x16x32_bf16 v[114:117], v[176:179], v[232:235], v[114:117]
	v_mfma_f32_16x16x32_bf16 v[102:105], v[146:149], v[240:243], v[102:105]
	v_mfma_f32_16x16x32_bf16 v[98:101], v[176:179], v[240:243], v[98:101]
	v_mfma_f32_16x16x32_bf16 v[70:73], v[172:175], v[218:221], v[70:73]
	v_mfma_f32_16x16x32_bf16 v[66:69], v[210:213], v[218:221], v[66:69]
	v_mfma_f32_16x16x32_bf16 v[34:37], v[172:175], v[228:231], v[34:37]
	v_mfma_f32_16x16x32_bf16 v[38:41], v[210:213], v[228:231], v[38:41]
	v_mfma_f32_16x16x32_bf16 v[118:121], v[172:175], v[236:239], v[118:121]
	v_mfma_f32_16x16x32_bf16 v[114:117], v[210:213], v[236:239], v[114:117]
	v_mfma_f32_16x16x32_bf16 v[102:105], v[172:175], v[244:247], v[102:105]
	v_mfma_f32_16x16x32_bf16 v[98:101], v[210:213], v[244:247], v[98:101]
	s_barrier
	s_setprio 0
	s_add_i32 s12, s17, s46
	v_lshl_add_u64 v[180:181], v[180:181], 0, s[30:31]
	s_mov_b32 m0, s12
	s_nop 0
	global_load_lds_dwordx4 v[180:181], off
	s_add_i32 m0, s12, 0x2000
	s_add_u32 s10, s10, 0x2b0080
	v_lshl_add_u64 v[180:181], v[248:249], 0, s[30:31]
	s_addc_u32 s11, s11, 0
	s_add_i32 s12, s18, s46
	global_load_lds_dwordx4 v[180:181], off
	v_lshl_add_u64 v[180:181], s[10:11], 0, v[150:151]
	s_mov_b32 m0, s12
	s_nop 0
	global_load_lds_dwordx4 v[180:181], off
	v_lshl_add_u64 v[180:181], s[10:11], 0, v[152:153]
	s_add_i32 m0, s12, 0x2000
	s_nop 0
	global_load_lds_dwordx4 v[180:181], off
	v_lshl_add_u64 v[180:181], v[250:251], 0, s[30:31]
	s_mov_b32 m0, s52
	s_nop 0
	global_load_lds_dwordx4 v[180:181], off
	v_lshl_add_u64 v[180:181], v[252:253], 0, s[30:31]
	s_mov_b32 m0, s53
	s_nop 0
	global_load_lds_dwordx4 v[180:181], off
	ds_read_b128 v[214:217], v202 offset:49152
	ds_read_b128 v[218:221], v202 offset:50176
	ds_read_b128 v[224:227], v202 offset:51200
	ds_read_b128 v[228:231], v202 offset:52224
	ds_read_b128 v[232:235], v202 offset:53248
	ds_read_b128 v[236:239], v202 offset:54272
	ds_read_b128 v[240:243], v202 offset:55296
	ds_read_b128 v[244:247], v202 offset:56320
	s_waitcnt vmcnt(8)
	s_waitcnt lgkmcnt(0)
	s_setprio 1
	s_barrier
	v_mfma_f32_16x16x32_bf16 v[94:97], v[130:133], v[214:217], v[94:97]
	v_mfma_f32_16x16x32_bf16 v[86:89], v[138:141], v[214:217], v[86:89]
	v_mfma_f32_16x16x32_bf16 v[82:85], v[130:133], v[224:227], v[82:85]
	v_mfma_f32_16x16x32_bf16 v[78:81], v[138:141], v[224:227], v[78:81]
	v_mfma_f32_16x16x32_bf16 v[30:33], v[130:133], v[232:235], v[30:33]
	v_mfma_f32_16x16x32_bf16 v[26:29], v[138:141], v[232:235], v[26:29]
	v_mfma_f32_16x16x32_bf16 v[22:25], v[130:133], v[240:243], v[22:25]
	v_mfma_f32_16x16x32_bf16 v[18:21], v[138:141], v[240:243], v[18:21]
	v_mfma_f32_16x16x32_bf16 v[94:97], v[134:137], v[218:221], v[94:97]
	v_mfma_f32_16x16x32_bf16 v[86:89], v[142:145], v[218:221], v[86:89]
	v_mfma_f32_16x16x32_bf16 v[82:85], v[134:137], v[228:231], v[82:85]
	v_mfma_f32_16x16x32_bf16 v[78:81], v[142:145], v[228:231], v[78:81]
	v_mfma_f32_16x16x32_bf16 v[30:33], v[134:137], v[236:239], v[30:33]
	v_mfma_f32_16x16x32_bf16 v[26:29], v[142:145], v[236:239], v[26:29]
	v_mfma_f32_16x16x32_bf16 v[22:25], v[134:137], v[244:247], v[22:25]
	v_mfma_f32_16x16x32_bf16 v[18:21], v[142:145], v[244:247], v[18:21]
	v_mfma_f32_16x16x32_bf16 v[62:65], v[146:149], v[214:217], v[62:65]
	v_mfma_f32_16x16x32_bf16 v[58:61], v[176:179], v[214:217], v[58:61]
	v_mfma_f32_16x16x32_bf16 v[54:57], v[146:149], v[224:227], v[54:57]
	v_mfma_f32_16x16x32_bf16 v[50:53], v[176:179], v[224:227], v[50:53]
	v_mfma_f32_16x16x32_bf16 v[14:17], v[146:149], v[232:235], v[14:17]
	v_mfma_f32_16x16x32_bf16 v[6:9], v[176:179], v[232:235], v[6:9]
	v_mfma_f32_16x16x32_bf16 v[10:13], v[146:149], v[240:243], v[10:13]
	v_mfma_f32_16x16x32_bf16 v[2:5], v[176:179], v[240:243], v[2:5]
	v_mfma_f32_16x16x32_bf16 v[62:65], v[172:175], v[218:221], v[62:65]
	v_mfma_f32_16x16x32_bf16 v[58:61], v[210:213], v[218:221], v[58:61]
	v_mfma_f32_16x16x32_bf16 v[54:57], v[172:175], v[228:231], v[54:57]
	v_mfma_f32_16x16x32_bf16 v[50:53], v[210:213], v[228:231], v[50:53]
	v_mfma_f32_16x16x32_bf16 v[14:17], v[172:175], v[236:239], v[14:17]
	v_mfma_f32_16x16x32_bf16 v[6:9], v[210:213], v[236:239], v[6:9]
	v_mfma_f32_16x16x32_bf16 v[10:13], v[172:175], v[244:247], v[10:13]
	v_mfma_f32_16x16x32_bf16 v[2:5], v[210:213], v[244:247], v[2:5]
	s_barrier
	s_setprio 0
	s_add_i32 s16, s16, 2
	s_add_u32 s8, s8, 0x100
	s_addc_u32 s9, s9, 0
	s_add_u32 s14, s14, 0x100
	s_addc_u32 s15, s15, 0
.LBB0_1040:
	s_add_u32 s10, s8, 0xffd50080
	s_addc_u32 s11, s9, -1
	s_cmpk_eq_i32 s16, 0xa8
	s_cselect_b32 s13, s25, s11
	s_cselect_b32 s12, s24, s10
	s_cselect_b32 s11, s41, s15
	s_cselect_b32 s10, s40, s14
	v_lshl_add_u64 v[180:181], s[8:9], 0, v[166:167]
	s_add_i32 m0, s48, 0xc000
	s_nop 0
	global_load_lds_dwordx4 v[180:181], off
	v_lshl_add_u64 v[180:181], s[8:9], 0, v[168:169]
	s_add_i32 m0, s48, 0xe000
	s_nop 0
	global_load_lds_dwordx4 v[180:181], off
	ds_read_b128 v[130:133], v207
	ds_read_b128 v[134:137], v207 offset:1024
	ds_read_b128 v[138:141], v207 offset:2048
	ds_read_b128 v[142:145], v207 offset:3072
	ds_read_b128 v[146:149], v208
	ds_read_b128 v[172:175], v208 offset:1024
	ds_read_b128 v[176:179], v208 offset:2048
	ds_read_b128 v[210:213], v208 offset:3072
	ds_read_b128 v[214:217], v202
	ds_read_b128 v[218:221], v202 offset:1024
	ds_read_b128 v[224:227], v202 offset:2048
	ds_read_b128 v[228:231], v202 offset:3072
	ds_read_b128 v[232:235], v202 offset:4096
	ds_read_b128 v[236:239], v202 offset:5120
	ds_read_b128 v[240:243], v202 offset:6144
	ds_read_b128 v[244:247], v202 offset:7168
	s_waitcnt vmcnt(8)
	s_waitcnt lgkmcnt(0)
	s_setprio 1
	s_barrier
	v_mfma_f32_16x16x32_bf16 v[90:93], v[130:133], v[214:217], v[90:93]
	v_mfma_f32_16x16x32_bf16 v[74:77], v[138:141], v[214:217], v[74:77]
	v_mfma_f32_16x16x32_bf16 v[46:49], v[130:133], v[224:227], v[46:49]
	v_mfma_f32_16x16x32_bf16 v[42:45], v[138:141], v[224:227], v[42:45]
	v_mfma_f32_16x16x32_bf16 v[126:129], v[130:133], v[232:235], v[126:129]
	v_mfma_f32_16x16x32_bf16 v[122:125], v[138:141], v[232:235], v[122:125]
	v_mfma_f32_16x16x32_bf16 v[110:113], v[130:133], v[240:243], v[110:113]
	v_mfma_f32_16x16x32_bf16 v[106:109], v[138:141], v[240:243], v[106:109]
	v_mfma_f32_16x16x32_bf16 v[90:93], v[134:137], v[218:221], v[90:93]
	v_mfma_f32_16x16x32_bf16 v[74:77], v[142:145], v[218:221], v[74:77]
	v_mfma_f32_16x16x32_bf16 v[46:49], v[134:137], v[228:231], v[46:49]
	v_mfma_f32_16x16x32_bf16 v[42:45], v[142:145], v[228:231], v[42:45]
	v_mfma_f32_16x16x32_bf16 v[126:129], v[134:137], v[236:239], v[126:129]
	v_mfma_f32_16x16x32_bf16 v[122:125], v[142:145], v[236:239], v[122:125]
	v_mfma_f32_16x16x32_bf16 v[110:113], v[134:137], v[244:247], v[110:113]
	v_mfma_f32_16x16x32_bf16 v[106:109], v[142:145], v[244:247], v[106:109]
	v_mfma_f32_16x16x32_bf16 v[70:73], v[146:149], v[214:217], v[70:73]
	v_mfma_f32_16x16x32_bf16 v[66:69], v[176:179], v[214:217], v[66:69]
	v_mfma_f32_16x16x32_bf16 v[34:37], v[146:149], v[224:227], v[34:37]
	v_mfma_f32_16x16x32_bf16 v[38:41], v[176:179], v[224:227], v[38:41]
	v_mfma_f32_16x16x32_bf16 v[118:121], v[146:149], v[232:235], v[118:121]
	v_mfma_f32_16x16x32_bf16 v[114:117], v[176:179], v[232:235], v[114:117]
	v_mfma_f32_16x16x32_bf16 v[102:105], v[146:149], v[240:243], v[102:105]
	v_mfma_f32_16x16x32_bf16 v[98:101], v[176:179], v[240:243], v[98:101]
	v_mfma_f32_16x16x32_bf16 v[70:73], v[172:175], v[218:221], v[70:73]
	v_mfma_f32_16x16x32_bf16 v[66:69], v[210:213], v[218:221], v[66:69]
	v_mfma_f32_16x16x32_bf16 v[34:37], v[172:175], v[228:231], v[34:37]
	v_mfma_f32_16x16x32_bf16 v[38:41], v[210:213], v[228:231], v[38:41]
	v_mfma_f32_16x16x32_bf16 v[118:121], v[172:175], v[236:239], v[118:121]
	v_mfma_f32_16x16x32_bf16 v[114:117], v[210:213], v[236:239], v[114:117]
	v_mfma_f32_16x16x32_bf16 v[102:105], v[172:175], v[244:247], v[102:105]
	v_mfma_f32_16x16x32_bf16 v[98:101], v[210:213], v[244:247], v[98:101]
	s_barrier
	s_setprio 0
	s_add_i32 s17, s57, s46
	v_lshl_add_u64 v[180:181], s[10:11], 0, v[150:151]
	s_mov_b32 m0, s17
	s_nop 0
	global_load_lds_dwordx4 v[180:181], off
	s_add_i32 m0, s17, 0x2000
	s_add_u32 s18, s10, 0x2b0000
	v_lshl_add_u64 v[248:249], s[10:11], 0, v[152:153]
	s_addc_u32 s19, s11, 0
	s_add_i32 s17, s58, s46
	global_load_lds_dwordx4 v[248:249], off
	v_lshl_add_u64 v[250:251], s[18:19], 0, v[150:151]
	s_mov_b32 m0, s17
	v_lshl_add_u64 v[252:253], s[12:13], 0, v[152:153]
	global_load_lds_dwordx4 v[250:251], off
	v_lshl_add_u64 v[250:251], s[18:19], 0, v[152:153]
	s_add_i32 m0, s17, 0x2000
	s_nop 0
	global_load_lds_dwordx4 v[250:251], off
	v_lshl_add_u64 v[250:251], s[12:13], 0, v[150:151]
	s_mov_b32 m0, s48
	s_nop 0
	global_load_lds_dwordx4 v[250:251], off
	s_mov_b32 m0, s49
	s_nop 0
	global_load_lds_dwordx4 v[252:253], off
	ds_read_b128 v[214:217], v202 offset:16384
	ds_read_b128 v[218:221], v202 offset:17408
	ds_read_b128 v[224:227], v202 offset:18432
	ds_read_b128 v[228:231], v202 offset:19456
	ds_read_b128 v[232:235], v202 offset:20480
	ds_read_b128 v[236:239], v202 offset:21504
	ds_read_b128 v[240:243], v202 offset:22528
	ds_read_b128 v[244:247], v202 offset:23552
	s_waitcnt vmcnt(8)
	s_waitcnt lgkmcnt(0)
	s_setprio 1
	s_barrier
	v_mfma_f32_16x16x32_bf16 v[94:97], v[130:133], v[214:217], v[94:97]
	v_mfma_f32_16x16x32_bf16 v[86:89], v[138:141], v[214:217], v[86:89]
	v_mfma_f32_16x16x32_bf16 v[82:85], v[130:133], v[224:227], v[82:85]
	v_mfma_f32_16x16x32_bf16 v[78:81], v[138:141], v[224:227], v[78:81]
	v_mfma_f32_16x16x32_bf16 v[30:33], v[130:133], v[232:235], v[30:33]
	v_mfma_f32_16x16x32_bf16 v[26:29], v[138:141], v[232:235], v[26:29]
	v_mfma_f32_16x16x32_bf16 v[22:25], v[130:133], v[240:243], v[22:25]
	v_mfma_f32_16x16x32_bf16 v[18:21], v[138:141], v[240:243], v[18:21]
	v_mfma_f32_16x16x32_bf16 v[94:97], v[134:137], v[218:221], v[94:97]
	v_mfma_f32_16x16x32_bf16 v[86:89], v[142:145], v[218:221], v[86:89]
	v_mfma_f32_16x16x32_bf16 v[82:85], v[134:137], v[228:231], v[82:85]
	v_mfma_f32_16x16x32_bf16 v[78:81], v[142:145], v[228:231], v[78:81]
	v_mfma_f32_16x16x32_bf16 v[30:33], v[134:137], v[236:239], v[30:33]
	v_mfma_f32_16x16x32_bf16 v[26:29], v[142:145], v[236:239], v[26:29]
	v_mfma_f32_16x16x32_bf16 v[22:25], v[134:137], v[244:247], v[22:25]
	v_mfma_f32_16x16x32_bf16 v[18:21], v[142:145], v[244:247], v[18:21]
	v_mfma_f32_16x16x32_bf16 v[62:65], v[146:149], v[214:217], v[62:65]
	v_mfma_f32_16x16x32_bf16 v[58:61], v[176:179], v[214:217], v[58:61]
	v_mfma_f32_16x16x32_bf16 v[54:57], v[146:149], v[224:227], v[54:57]
	v_mfma_f32_16x16x32_bf16 v[50:53], v[176:179], v[224:227], v[50:53]
	v_mfma_f32_16x16x32_bf16 v[14:17], v[146:149], v[232:235], v[14:17]
	v_mfma_f32_16x16x32_bf16 v[6:9], v[176:179], v[232:235], v[6:9]
	v_mfma_f32_16x16x32_bf16 v[10:13], v[146:149], v[240:243], v[10:13]
	v_mfma_f32_16x16x32_bf16 v[2:5], v[176:179], v[240:243], v[2:5]
	v_mfma_f32_16x16x32_bf16 v[62:65], v[172:175], v[218:221], v[62:65]
	v_mfma_f32_16x16x32_bf16 v[58:61], v[210:213], v[218:221], v[58:61]
	v_mfma_f32_16x16x32_bf16 v[54:57], v[172:175], v[228:231], v[54:57]
	v_mfma_f32_16x16x32_bf16 v[50:53], v[210:213], v[228:231], v[50:53]
	v_mfma_f32_16x16x32_bf16 v[14:17], v[172:175], v[236:239], v[14:17]
	v_mfma_f32_16x16x32_bf16 v[6:9], v[210:213], v[236:239], v[6:9]
	v_mfma_f32_16x16x32_bf16 v[10:13], v[172:175], v[244:247], v[10:13]
	v_mfma_f32_16x16x32_bf16 v[2:5], v[210:213], v[244:247], v[2:5]
	s_barrier
	s_setprio 0
	s_add_i32 s17, 0, 0x18000
	s_add_i32 s18, 0, 0x1c000
	v_add_u32_e32 v142, s17, v182
	v_add_u32_e32 v154, s18, v182
	s_add_u32 s12, s12, 0x2b0000
	s_addc_u32 s13, s13, 0
	s_mov_b32 m0, s50
	v_lshl_add_u64 v[188:189], s[12:13], 0, v[150:151]
	global_load_lds_dwordx4 v[188:189], off
	v_lshl_add_u64 v[188:189], s[12:13], 0, v[152:153]
	s_mov_b32 m0, s51
	s_nop 0
	global_load_lds_dwordx4 v[188:189], off
	ds_read_b128 v[130:133], v142
	ds_read_b128 v[134:137], v142 offset:1024
	ds_read_b128 v[138:141], v142 offset:2048
	ds_read_b128 v[142:145], v142 offset:3072
	ds_read_b128 v[146:149], v154
	ds_read_b128 v[172:175], v154 offset:1024
	ds_read_b128 v[176:179], v154 offset:2048
	ds_read_b128 v[210:213], v154 offset:3072
	ds_read_b128 v[214:217], v202 offset:32768
	ds_read_b128 v[218:221], v202 offset:33792
	ds_read_b128 v[224:227], v202 offset:34816
	ds_read_b128 v[228:231], v202 offset:35840
	ds_read_b128 v[232:235], v202 offset:36864
	ds_read_b128 v[236:239], v202 offset:37888
	ds_read_b128 v[240:243], v202 offset:38912
	ds_read_b128 v[244:247], v202 offset:39936
	s_waitcnt vmcnt(8)
	s_waitcnt lgkmcnt(0)
	s_setprio 1
	s_barrier
	v_mfma_f32_16x16x32_bf16 v[90:93], v[130:133], v[214:217], v[90:93]
	v_mfma_f32_16x16x32_bf16 v[74:77], v[138:141], v[214:217], v[74:77]
	v_mfma_f32_16x16x32_bf16 v[46:49], v[130:133], v[224:227], v[46:49]
	v_mfma_f32_16x16x32_bf16 v[42:45], v[138:141], v[224:227], v[42:45]
	v_mfma_f32_16x16x32_bf16 v[126:129], v[130:133], v[232:235], v[126:129]
	v_mfma_f32_16x16x32_bf16 v[122:125], v[138:141], v[232:235], v[122:125]
	v_mfma_f32_16x16x32_bf16 v[110:113], v[130:133], v[240:243], v[110:113]
	v_mfma_f32_16x16x32_bf16 v[106:109], v[138:141], v[240:243], v[106:109]
	v_mfma_f32_16x16x32_bf16 v[90:93], v[134:137], v[218:221], v[90:93]
	v_mfma_f32_16x16x32_bf16 v[74:77], v[142:145], v[218:221], v[74:77]
	v_mfma_f32_16x16x32_bf16 v[46:49], v[134:137], v[228:231], v[46:49]
	v_mfma_f32_16x16x32_bf16 v[42:45], v[142:145], v[228:231], v[42:45]
	v_mfma_f32_16x16x32_bf16 v[126:129], v[134:137], v[236:239], v[126:129]
	v_mfma_f32_16x16x32_bf16 v[122:125], v[142:145], v[236:239], v[122:125]
	v_mfma_f32_16x16x32_bf16 v[110:113], v[134:137], v[244:247], v[110:113]
	v_mfma_f32_16x16x32_bf16 v[106:109], v[142:145], v[244:247], v[106:109]
	v_mfma_f32_16x16x32_bf16 v[70:73], v[146:149], v[214:217], v[70:73]
	v_mfma_f32_16x16x32_bf16 v[66:69], v[176:179], v[214:217], v[66:69]
	v_mfma_f32_16x16x32_bf16 v[34:37], v[146:149], v[224:227], v[34:37]
	v_mfma_f32_16x16x32_bf16 v[38:41], v[176:179], v[224:227], v[38:41]
	v_mfma_f32_16x16x32_bf16 v[118:121], v[146:149], v[232:235], v[118:121]
	v_mfma_f32_16x16x32_bf16 v[114:117], v[176:179], v[232:235], v[114:117]
	v_mfma_f32_16x16x32_bf16 v[102:105], v[146:149], v[240:243], v[102:105]
	v_mfma_f32_16x16x32_bf16 v[98:101], v[176:179], v[240:243], v[98:101]
	v_mfma_f32_16x16x32_bf16 v[70:73], v[172:175], v[218:221], v[70:73]
	v_mfma_f32_16x16x32_bf16 v[66:69], v[210:213], v[218:221], v[66:69]
	v_mfma_f32_16x16x32_bf16 v[34:37], v[172:175], v[228:231], v[34:37]
	v_mfma_f32_16x16x32_bf16 v[38:41], v[210:213], v[228:231], v[38:41]
	v_mfma_f32_16x16x32_bf16 v[118:121], v[172:175], v[236:239], v[118:121]
	v_mfma_f32_16x16x32_bf16 v[114:117], v[210:213], v[236:239], v[114:117]
	v_mfma_f32_16x16x32_bf16 v[102:105], v[172:175], v[244:247], v[102:105]
	v_mfma_f32_16x16x32_bf16 v[98:101], v[210:213], v[244:247], v[98:101]
	s_barrier
	s_setprio 0
	s_add_i32 s12, s17, s46
	v_lshl_add_u64 v[180:181], v[180:181], 0, s[30:31]
	s_mov_b32 m0, s12
	s_nop 0
	global_load_lds_dwordx4 v[180:181], off
	s_add_i32 m0, s12, 0x2000
	s_add_u32 s10, s10, 0x2b0080
	v_lshl_add_u64 v[180:181], v[248:249], 0, s[30:31]
	s_addc_u32 s11, s11, 0
	s_add_i32 s12, s18, s46
	global_load_lds_dwordx4 v[180:181], off
	v_lshl_add_u64 v[180:181], s[10:11], 0, v[150:151]
	s_mov_b32 m0, s12
	s_nop 0
	global_load_lds_dwordx4 v[180:181], off
	v_lshl_add_u64 v[180:181], s[10:11], 0, v[152:153]
	s_add_i32 m0, s12, 0x2000
	s_nop 0
	global_load_lds_dwordx4 v[180:181], off
	v_lshl_add_u64 v[180:181], v[250:251], 0, s[30:31]
	s_mov_b32 m0, s52
	s_nop 0
	global_load_lds_dwordx4 v[180:181], off
	v_lshl_add_u64 v[180:181], v[252:253], 0, s[30:31]
	s_mov_b32 m0, s53
	s_nop 0
	global_load_lds_dwordx4 v[180:181], off
	ds_read_b128 v[214:217], v202 offset:49152
	ds_read_b128 v[218:221], v202 offset:50176
	ds_read_b128 v[224:227], v202 offset:51200
	ds_read_b128 v[228:231], v202 offset:52224
	ds_read_b128 v[232:235], v202 offset:53248
	ds_read_b128 v[236:239], v202 offset:54272
	ds_read_b128 v[240:243], v202 offset:55296
	ds_read_b128 v[244:247], v202 offset:56320
	s_waitcnt vmcnt(8)
	s_waitcnt lgkmcnt(0)
	s_setprio 1
	s_barrier
	v_mfma_f32_16x16x32_bf16 v[94:97], v[130:133], v[214:217], v[94:97]
	v_mfma_f32_16x16x32_bf16 v[86:89], v[138:141], v[214:217], v[86:89]
	v_mfma_f32_16x16x32_bf16 v[82:85], v[130:133], v[224:227], v[82:85]
	v_mfma_f32_16x16x32_bf16 v[78:81], v[138:141], v[224:227], v[78:81]
	v_mfma_f32_16x16x32_bf16 v[30:33], v[130:133], v[232:235], v[30:33]
	v_mfma_f32_16x16x32_bf16 v[26:29], v[138:141], v[232:235], v[26:29]
	v_mfma_f32_16x16x32_bf16 v[22:25], v[130:133], v[240:243], v[22:25]
	v_mfma_f32_16x16x32_bf16 v[18:21], v[138:141], v[240:243], v[18:21]
	v_mfma_f32_16x16x32_bf16 v[94:97], v[134:137], v[218:221], v[94:97]
	v_mfma_f32_16x16x32_bf16 v[86:89], v[142:145], v[218:221], v[86:89]
	v_mfma_f32_16x16x32_bf16 v[82:85], v[134:137], v[228:231], v[82:85]
	v_mfma_f32_16x16x32_bf16 v[78:81], v[142:145], v[228:231], v[78:81]
	v_mfma_f32_16x16x32_bf16 v[30:33], v[134:137], v[236:239], v[30:33]
	v_mfma_f32_16x16x32_bf16 v[26:29], v[142:145], v[236:239], v[26:29]
	v_mfma_f32_16x16x32_bf16 v[22:25], v[134:137], v[244:247], v[22:25]
	v_mfma_f32_16x16x32_bf16 v[18:21], v[142:145], v[244:247], v[18:21]
	v_mfma_f32_16x16x32_bf16 v[62:65], v[146:149], v[214:217], v[62:65]
	v_mfma_f32_16x16x32_bf16 v[58:61], v[176:179], v[214:217], v[58:61]
	v_mfma_f32_16x16x32_bf16 v[54:57], v[146:149], v[224:227], v[54:57]
	v_mfma_f32_16x16x32_bf16 v[50:53], v[176:179], v[224:227], v[50:53]
	v_mfma_f32_16x16x32_bf16 v[14:17], v[146:149], v[232:235], v[14:17]
	v_mfma_f32_16x16x32_bf16 v[6:9], v[176:179], v[232:235], v[6:9]
	v_mfma_f32_16x16x32_bf16 v[10:13], v[146:149], v[240:243], v[10:13]
	v_mfma_f32_16x16x32_bf16 v[2:5], v[176:179], v[240:243], v[2:5]
	v_mfma_f32_16x16x32_bf16 v[62:65], v[172:175], v[218:221], v[62:65]
	v_mfma_f32_16x16x32_bf16 v[58:61], v[210:213], v[218:221], v[58:61]
	v_mfma_f32_16x16x32_bf16 v[54:57], v[172:175], v[228:231], v[54:57]
	v_mfma_f32_16x16x32_bf16 v[50:53], v[210:213], v[228:231], v[50:53]
	v_mfma_f32_16x16x32_bf16 v[14:17], v[172:175], v[236:239], v[14:17]
	v_mfma_f32_16x16x32_bf16 v[6:9], v[210:213], v[236:239], v[6:9]
	v_mfma_f32_16x16x32_bf16 v[10:13], v[172:175], v[244:247], v[10:13]
	v_mfma_f32_16x16x32_bf16 v[2:5], v[210:213], v[244:247], v[2:5]
	s_barrier
	s_setprio 0
	s_add_i32 s16, s16, 2
	s_add_u32 s8, s8, 0x100
	s_addc_u32 s9, s9, 0
	s_add_u32 s14, s14, 0x100
	s_addc_u32 s15, s15, 0
	s_cmpk_gt_u32 s16, 0xa9
	s_cbranch_scc0 .LBB0_1040
	s_and_b64 vcc, exec, s[34:35]
	s_cbranch_vccz .LBB0_1043
	s_barrier
